# as C1 plus: GLA-out unit keeps its start-state loads in flight across tile staging; redundant mid-segment s_setprio pairs removed
# speedup vs baseline: 1.0013x; 1.0013x over previous
; #define PG8_STAGE(bufoff, gbase, voff) do { _Pragma("unroll") for (int _i = 0; _i < 2; ++_i) \
;         __builtin_amdgcn_global_load_lds((const unsigned*)((const char*)(gbase) + (voff)[_i]), (PG8_LAS unsigned*)(lds + (bufoff) + ldsw + _i * 8192), 16, 0, 0); } while (0)
; #define PG8_LDA(dst, b, h) do { _Pragma("unroll") for (int m = 0; m < 4; ++m) _Pragma("unroll") for (int k = 0; k < 2; ++k) dst[m][k] = *(const PG8_LAS bf16x8*)(lds + PG8_SA(b, h) + aoff + m * 2048 + k * 1024); } while (0)
; #define PG8_WAIT_V(n) asm volatile("s_waitcnt vmcnt(" #n ")" ::: "memory")
; #define PG8_WAIT_L(n) asm volatile("s_waitcnt lgkmcnt(" #n ")" ::: "memory")
; template <class Epi, class Sched, bool ALIGN_EPI = false, bool SP2 = false, bool ABLK = false, bool BBLK = false>
; __device__ __forceinline__ void gemm_phase(PG8_LAS unsigned char* lds, const Gemm g, const Sched& S, const Epi& E) {
;     ...
;         for (int t = 0; t < nt; t += 2) {
;             const bool last = (t == nt - 2);
;             const char* a1 = cA + (size_t)(t + 1) * kstepA;
;             const char* a2 = last ? nA : cA + (size_t)(t + 2) * kstepA; const char* b2 = last ? nB : cB + (size_t)(t + 2) * kstepB;
;             const char* a3 = a2 + kstepA; const char* b3 = b2 + kstepB;
;             if (last && has_next) S.a_ready(nxt);
;             if constexpr (SP2) {
;             PG8_LDB(B0, 0, 0); PG8_LDB(B1, 0, 1); PG8_SCHED; PG8_LDA(At, 0, 0); PG8_STAGE(PG8_SA(1, 1), a1 + hstepA, voffA);
;             PG8_WAIT_V(8); PG8_WAIT_L(0); PG8_BAR; PG8_MMA(0, 0, At, B0); PG8_MMA(0, 1, At, B1); PG8_BAR; PG8_SCHED;
;             PG8_LDA(At, 0, 1); PG8_STAGE(PG8_SB(0, 0), b2, voffB); PG8_STAGE(PG8_SB(0, 1), b2 + hstepB, voffB); PG8_STAGE(PG8_SA(0, 0), a2, voffA);
;             PG8_WAIT_V(8); PG8_WAIT_L(0); PG8_BAR; PG8_MMA(1, 0, At, B0); PG8_MMA(1, 1, At, B1); PG8_BAR; PG8_SCHED;
;             PG8_LDB(B0, 1, 0); PG8_LDB(B1, 1, 1); PG8_SCHED; PG8_LDA(At, 1, 0); PG8_STAGE(PG8_SA(0, 1), a2 + hstepA, voffA);
;             PG8_WAIT_V(8); PG8_WAIT_L(0); PG8_BAR; PG8_MMA(0, 0, At, B0); PG8_MMA(0, 1, At, B1); PG8_BAR; PG8_SCHED;
;             PG8_LDA(At, 1, 1); PG8_STAGE(PG8_SB(1, 0), b3, voffB); PG8_STAGE(PG8_SB(1, 1), b3 + hstepB, voffB); PG8_STAGE(PG8_SA(1, 0), a3, voffA);
;             PG8_WAIT_V(8); PG8_WAIT_L(0); PG8_BAR; PG8_MMA(1, 0, At, B0); PG8_MMA(1, 1, At, B1); PG8_BAR; PG8_SCHED;
.LBB0_185:
	s_add_u32 s13, s20, 0x4000
	s_addc_u32 s22, s21, 0
	s_cmp_eq_u32 vcc_hi, 28
	s_cselect_b32 s26, s70, s13
	s_cselect_b32 s27, s9, s22
	s_cselect_b32 s24, s71, s77
	s_cselect_b32 s25, s7, vcc_lo
	s_add_u32 s22, s26, 0x8000
	s_addc_u32 s23, s27, 0
	s_add_i32 s13, 0, 0x10000
	v_add_u32_e32 v36, s13, v160
	s_add_i32 s88, 0, 0x14000
	ds_read_b128 v[152:155], v36
	ds_read_b128 v[156:159], v36 offset:1024
	ds_read_b128 v[162:165], v36 offset:2048
	ds_read_b128 v[166:169], v36 offset:3072
	v_add_u32_e32 v36, s88, v160
	ds_read_b128 v[170:173], v36
	ds_read_b128 v[174:177], v36 offset:1024
	ds_read_b128 v[178:181], v36 offset:2048
	ds_read_b128 v[182:185], v36 offset:3072
	s_add_i32 m0, s19, 0xc000
	ds_read_b128 v[186:189], v161
	ds_read_b128 v[190:193], v161 offset:1024
	ds_read_b128 v[194:197], v161 offset:2048
	ds_read_b128 v[198:201], v161 offset:3072
	ds_read_b128 v[202:205], v161 offset:4096
	ds_read_b128 v[206:209], v161 offset:5120
	ds_read_b128 v[210:213], v161 offset:6144
	ds_read_b128 v[214:217], v161 offset:7168
	global_load_lds_dwordx4 v148, s[20:21]
	s_add_i32 m0, s19, 0xe000
	s_nop 0
	global_load_lds_dwordx4 v150, s[20:21]
	s_waitcnt vmcnt(8)
	s_waitcnt lgkmcnt(0)
	v_mfma_f32_16x16x32_bf16 v[132:135], v[152:155], v[186:189], v[132:135]
	v_mfma_f32_16x16x32_bf16 v[128:131], v[162:165], v[186:189], v[128:131]
	v_mfma_f32_16x16x32_bf16 v[116:119], v[152:155], v[194:197], v[116:119]
	v_mfma_f32_16x16x32_bf16 v[112:115], v[162:165], v[194:197], v[112:115]
	s_barrier
	s_setprio 1
	v_mfma_f32_16x16x32_bf16 v[100:103], v[152:155], v[202:205], v[100:103]
	v_mfma_f32_16x16x32_bf16 v[96:99], v[162:165], v[202:205], v[96:99]
	v_mfma_f32_16x16x32_bf16 v[84:87], v[152:155], v[210:213], v[84:87]
	v_mfma_f32_16x16x32_bf16 v[80:83], v[162:165], v[210:213], v[80:83]
	v_mfma_f32_16x16x32_bf16 v[132:135], v[156:159], v[190:193], v[132:135]
	v_mfma_f32_16x16x32_bf16 v[128:131], v[166:169], v[190:193], v[128:131]
	v_mfma_f32_16x16x32_bf16 v[116:119], v[156:159], v[198:201], v[116:119]
	v_mfma_f32_16x16x32_bf16 v[112:115], v[166:169], v[198:201], v[112:115]
	v_mfma_f32_16x16x32_bf16 v[100:103], v[156:159], v[206:209], v[100:103]
	v_mfma_f32_16x16x32_bf16 v[96:99], v[166:169], v[206:209], v[96:99]
	v_mfma_f32_16x16x32_bf16 v[84:87], v[156:159], v[214:217], v[84:87]
	v_mfma_f32_16x16x32_bf16 v[80:83], v[166:169], v[214:217], v[80:83]
	v_mfma_f32_16x16x32_bf16 v[124:127], v[170:173], v[186:189], v[124:127]
	v_mfma_f32_16x16x32_bf16 v[120:123], v[178:181], v[186:189], v[120:123]
	v_mfma_f32_16x16x32_bf16 v[108:111], v[170:173], v[194:197], v[108:111]
	v_mfma_f32_16x16x32_bf16 v[104:107], v[178:181], v[194:197], v[104:107]
	v_mfma_f32_16x16x32_bf16 v[92:95], v[170:173], v[202:205], v[92:95]
	v_mfma_f32_16x16x32_bf16 v[88:91], v[178:181], v[202:205], v[88:91]
	v_mfma_f32_16x16x32_bf16 v[76:79], v[170:173], v[210:213], v[76:79]
	v_mfma_f32_16x16x32_bf16 v[72:75], v[178:181], v[210:213], v[72:75]
	v_mfma_f32_16x16x32_bf16 v[124:127], v[174:177], v[190:193], v[124:127]
	v_mfma_f32_16x16x32_bf16 v[120:123], v[182:185], v[190:193], v[120:123]
	v_mfma_f32_16x16x32_bf16 v[108:111], v[174:177], v[198:201], v[108:111]
	v_mfma_f32_16x16x32_bf16 v[104:107], v[182:185], v[198:201], v[104:107]
	v_mfma_f32_16x16x32_bf16 v[92:95], v[174:177], v[206:209], v[92:95]
	v_mfma_f32_16x16x32_bf16 v[88:91], v[182:185], v[206:209], v[88:91]
	v_mfma_f32_16x16x32_bf16 v[76:79], v[174:177], v[214:217], v[76:79]
	v_mfma_f32_16x16x32_bf16 v[72:75], v[182:185], v[214:217], v[72:75]
	s_setprio 0
	s_barrier
	s_add_i32 s13, s13, s31
	s_mov_b32 m0, s13
	ds_read_b128 v[186:189], v161 offset:16384
	ds_read_b128 v[190:193], v161 offset:17408
	ds_read_b128 v[194:197], v161 offset:18432
	ds_read_b128 v[198:201], v161 offset:19456
	ds_read_b128 v[202:205], v161 offset:20480
	ds_read_b128 v[206:209], v161 offset:21504
	ds_read_b128 v[210:213], v161 offset:22528
	ds_read_b128 v[214:217], v161 offset:23552
	global_load_lds_dwordx4 v140, s[24:25]
	s_add_i32 m0, s13, 0x2000
	s_add_u32 s68, s24, 0x4000
	s_addc_u32 s69, s25, 0
	s_add_i32 s13, s88, s31
	global_load_lds_dwordx4 v136, s[24:25]
	s_mov_b32 m0, s13
	s_nop 0
	global_load_lds_dwordx4 v140, s[68:69]
	s_add_i32 m0, s13, 0x2000
	s_nop 0
	global_load_lds_dwordx4 v136, s[68:69]
	s_mov_b32 m0, s19
	s_nop 0
	global_load_lds_dwordx4 v142, s[26:27]
	s_mov_b32 m0, s35
	s_nop 0
	global_load_lds_dwordx4 v138, s[26:27]
	s_waitcnt vmcnt(8)
	s_waitcnt lgkmcnt(0)
	v_mfma_f32_16x16x32_bf16 v[68:71], v[152:155], v[186:189], v[68:71]
	v_mfma_f32_16x16x32_bf16 v[64:67], v[162:165], v[186:189], v[64:67]
	v_mfma_f32_16x16x32_bf16 v[52:55], v[152:155], v[194:197], v[52:55]
	v_mfma_f32_16x16x32_bf16 v[48:51], v[162:165], v[194:197], v[48:51]
	s_barrier
; #define PG8_STAGE(bufoff, gbase, voff) do { _Pragma("unroll") for (int _i = 0; _i < 2; ++_i) \
;         __builtin_amdgcn_global_load_lds((const unsigned*)((const char*)(gbase) + (voff)[_i]), (PG8_LAS unsigned*)(lds + (bufoff) + ldsw + _i * 8192), 16, 0, 0); } while (0)
; #define PG8_LDA(dst, b, h) do { _Pragma("unroll") for (int m = 0; m < 4; ++m) _Pragma("unroll") for (int k = 0; k < 2; ++k) dst[m][k] = *(const PG8_LAS bf16x8*)(lds + PG8_SA(b, h) + aoff + m * 2048 + k * 1024); } while (0)
; #define PG8_LDB(dst, b, h) do { _Pragma("unroll") for (int n = 0; n < 2; ++n) _Pragma("unroll") for (int k = 0; k < 2; ++k) dst[n][k] = *(const PG8_LAS bf16x8*)(lds + PG8_SB(b, h) + boff + n * 2048 + k * 1024); } while (0)
; #define PG8_MMA(ai, bj, At, Bt) do { __builtin_amdgcn_s_setprio(1); _Pragma("unroll") for (int m = 0; m < 4; ++m) _Pragma("unroll") for (int n = 0; n < 2; ++n) _Pragma("unroll") for (int k = 0; k < 2; ++k) \
;         acc[ai][bj][m][n] = __builtin_amdgcn_mfma_f32_16x16x32_bf16(Bt[n][k], At[m][k], acc[ai][bj][m][n], 0, 0, 0); __builtin_amdgcn_s_setprio(0); } while (0)
; template <class Epi, class Sched, bool ALIGN_EPI = false, bool SP2 = false, bool ABLK = false, bool BBLK = false>
; __device__ __forceinline__ void gemm_phase(PG8_LAS unsigned char* lds, const Gemm g, const Sched& S, const Epi& E) {
;     ...
;             PG8_LDB(B0, 0, 0); PG8_LDB(B1, 0, 1); PG8_SCHED; PG8_LDA(At, 0, 0); PG8_STAGE(PG8_SA(1, 1), a1 + hstepA, voffA);
;             PG8_WAIT_V(8); PG8_WAIT_L(0); PG8_BAR; PG8_MMA(0, 0, At, B0); PG8_MMA(0, 1, At, B1); PG8_BAR; PG8_SCHED;
;             PG8_LDA(At, 0, 1); PG8_STAGE(PG8_SB(0, 0), b2, voffB); PG8_STAGE(PG8_SB(0, 1), b2 + hstepB, voffB); PG8_STAGE(PG8_SA(0, 0), a2, voffA);
;             PG8_WAIT_V(8); PG8_WAIT_L(0); PG8_BAR; PG8_MMA(1, 0, At, B0); PG8_MMA(1, 1, At, B1); PG8_BAR; PG8_SCHED;
;             PG8_LDB(B0, 1, 0); PG8_LDB(B1, 1, 1); PG8_SCHED; PG8_LDA(At, 1, 0); PG8_STAGE(PG8_SA(0, 1), a2 + hstepA, voffA);
;             PG8_WAIT_V(8); PG8_WAIT_L(0); PG8_BAR; PG8_MMA(0, 0, At, B0); PG8_MMA(0, 1, At, B1); PG8_BAR; PG8_SCHED;
;             PG8_LDA(At, 1, 1); PG8_STAGE(PG8_SB(1, 0), b3, voffB); PG8_STAGE(PG8_SB(1, 1), b3 + hstepB, voffB); PG8_STAGE(PG8_SA(1, 0), a3, voffA);
;             PG8_WAIT_V(8); PG8_WAIT_L(0); PG8_BAR; PG8_MMA(1, 0, At, B0); PG8_MMA(1, 1, At, B1); PG8_BAR; PG8_SCHED;
	s_setprio 1
	v_mfma_f32_16x16x32_bf16 v[32:35], v[152:155], v[202:205], v[32:35]
	v_mfma_f32_16x16x32_bf16 v[28:31], v[162:165], v[202:205], v[28:31]
	v_mfma_f32_16x16x32_bf16 v[16:19], v[152:155], v[210:213], v[16:19]
	v_mfma_f32_16x16x32_bf16 v[12:15], v[162:165], v[210:213], v[12:15]
	v_mfma_f32_16x16x32_bf16 v[68:71], v[156:159], v[190:193], v[68:71]
	v_mfma_f32_16x16x32_bf16 v[64:67], v[166:169], v[190:193], v[64:67]
	v_mfma_f32_16x16x32_bf16 v[52:55], v[156:159], v[198:201], v[52:55]
	v_mfma_f32_16x16x32_bf16 v[48:51], v[166:169], v[198:201], v[48:51]
	v_mfma_f32_16x16x32_bf16 v[32:35], v[156:159], v[206:209], v[32:35]
	v_mfma_f32_16x16x32_bf16 v[28:31], v[166:169], v[206:209], v[28:31]
	v_mfma_f32_16x16x32_bf16 v[16:19], v[156:159], v[214:217], v[16:19]
	v_mfma_f32_16x16x32_bf16 v[12:15], v[166:169], v[214:217], v[12:15]
	v_mfma_f32_16x16x32_bf16 v[60:63], v[170:173], v[186:189], v[60:63]
	v_mfma_f32_16x16x32_bf16 v[56:59], v[178:181], v[186:189], v[56:59]
	v_mfma_f32_16x16x32_bf16 v[44:47], v[170:173], v[194:197], v[44:47]
	v_mfma_f32_16x16x32_bf16 v[40:43], v[178:181], v[194:197], v[40:43]
	v_mfma_f32_16x16x32_bf16 v[24:27], v[170:173], v[202:205], v[24:27]
	v_mfma_f32_16x16x32_bf16 v[20:23], v[178:181], v[202:205], v[20:23]
	v_mfma_f32_16x16x32_bf16 v[8:11], v[170:173], v[210:213], v[8:11]
	v_mfma_f32_16x16x32_bf16 v[4:7], v[178:181], v[210:213], v[4:7]
	v_mfma_f32_16x16x32_bf16 v[60:63], v[174:177], v[190:193], v[60:63]
	v_mfma_f32_16x16x32_bf16 v[56:59], v[182:185], v[190:193], v[56:59]
	v_mfma_f32_16x16x32_bf16 v[44:47], v[174:177], v[198:201], v[44:47]
	v_mfma_f32_16x16x32_bf16 v[40:43], v[182:185], v[198:201], v[40:43]
	v_mfma_f32_16x16x32_bf16 v[24:27], v[174:177], v[206:209], v[24:27]
	v_mfma_f32_16x16x32_bf16 v[20:23], v[182:185], v[206:209], v[20:23]
	v_mfma_f32_16x16x32_bf16 v[8:11], v[174:177], v[214:217], v[8:11]
	v_mfma_f32_16x16x32_bf16 v[4:7], v[182:185], v[214:217], v[4:7]
	s_setprio 0
	s_barrier
	s_add_i32 s13, 0, 0x18000
	v_add_u32_e32 v36, s13, v160
	s_add_i32 s68, 0, 0x1c000
	ds_read_b128 v[152:155], v36
	ds_read_b128 v[156:159], v36 offset:1024
	ds_read_b128 v[162:165], v36 offset:2048
	ds_read_b128 v[166:169], v36 offset:3072
	v_add_u32_e32 v36, s68, v160
	ds_read_b128 v[170:173], v36
	ds_read_b128 v[174:177], v36 offset:1024
	ds_read_b128 v[178:181], v36 offset:2048
	ds_read_b128 v[182:185], v36 offset:3072
	s_add_u32 s26, s26, 0x4000
	s_addc_u32 s27, s27, 0
	s_mov_b32 m0, s36
	ds_read_b128 v[186:189], v161 offset:32768
	ds_read_b128 v[190:193], v161 offset:33792
	ds_read_b128 v[194:197], v161 offset:34816
	ds_read_b128 v[198:201], v161 offset:35840
	ds_read_b128 v[202:205], v161 offset:36864
	ds_read_b128 v[206:209], v161 offset:37888
	ds_read_b128 v[210:213], v161 offset:38912
	ds_read_b128 v[214:217], v161 offset:39936
	global_load_lds_dwordx4 v142, s[26:27]
	s_mov_b32 m0, s37
	s_nop 0
	global_load_lds_dwordx4 v138, s[26:27]
	s_waitcnt vmcnt(8)
	s_waitcnt lgkmcnt(0)
	v_mfma_f32_16x16x32_bf16 v[132:135], v[152:155], v[186:189], v[132:135]
	v_mfma_f32_16x16x32_bf16 v[128:131], v[162:165], v[186:189], v[128:131]
	v_mfma_f32_16x16x32_bf16 v[116:119], v[152:155], v[194:197], v[116:119]
	v_mfma_f32_16x16x32_bf16 v[112:115], v[162:165], v[194:197], v[112:115]
	s_barrier
	s_setprio 1
	v_mfma_f32_16x16x32_bf16 v[100:103], v[152:155], v[202:205], v[100:103]
	v_mfma_f32_16x16x32_bf16 v[96:99], v[162:165], v[202:205], v[96:99]
	v_mfma_f32_16x16x32_bf16 v[84:87], v[152:155], v[210:213], v[84:87]
	v_mfma_f32_16x16x32_bf16 v[80:83], v[162:165], v[210:213], v[80:83]
	v_mfma_f32_16x16x32_bf16 v[132:135], v[156:159], v[190:193], v[132:135]
	v_mfma_f32_16x16x32_bf16 v[128:131], v[166:169], v[190:193], v[128:131]
	v_mfma_f32_16x16x32_bf16 v[116:119], v[156:159], v[198:201], v[116:119]
	v_mfma_f32_16x16x32_bf16 v[112:115], v[166:169], v[198:201], v[112:115]
	v_mfma_f32_16x16x32_bf16 v[100:103], v[156:159], v[206:209], v[100:103]
	v_mfma_f32_16x16x32_bf16 v[96:99], v[166:169], v[206:209], v[96:99]
	v_mfma_f32_16x16x32_bf16 v[84:87], v[156:159], v[214:217], v[84:87]
	v_mfma_f32_16x16x32_bf16 v[80:83], v[166:169], v[214:217], v[80:83]
	v_mfma_f32_16x16x32_bf16 v[124:127], v[170:173], v[186:189], v[124:127]
	v_mfma_f32_16x16x32_bf16 v[120:123], v[178:181], v[186:189], v[120:123]
	v_mfma_f32_16x16x32_bf16 v[108:111], v[170:173], v[194:197], v[108:111]
	v_mfma_f32_16x16x32_bf16 v[104:107], v[178:181], v[194:197], v[104:107]
	v_mfma_f32_16x16x32_bf16 v[92:95], v[170:173], v[202:205], v[92:95]
	v_mfma_f32_16x16x32_bf16 v[88:91], v[178:181], v[202:205], v[88:91]
	v_mfma_f32_16x16x32_bf16 v[76:79], v[170:173], v[210:213], v[76:79]
	v_mfma_f32_16x16x32_bf16 v[72:75], v[178:181], v[210:213], v[72:75]
	v_mfma_f32_16x16x32_bf16 v[124:127], v[174:177], v[190:193], v[124:127]
	v_mfma_f32_16x16x32_bf16 v[120:123], v[182:185], v[190:193], v[120:123]
	v_mfma_f32_16x16x32_bf16 v[108:111], v[174:177], v[198:201], v[108:111]
	v_mfma_f32_16x16x32_bf16 v[104:107], v[182:185], v[198:201], v[104:107]
	v_mfma_f32_16x16x32_bf16 v[92:95], v[174:177], v[206:209], v[92:95]
	v_mfma_f32_16x16x32_bf16 v[88:91], v[182:185], v[206:209], v[88:91]
	v_mfma_f32_16x16x32_bf16 v[76:79], v[174:177], v[214:217], v[76:79]
	v_mfma_f32_16x16x32_bf16 v[72:75], v[182:185], v[214:217], v[72:75]
	s_setprio 0
	s_barrier
; #define PG8_STAGE(bufoff, gbase, voff) do { _Pragma("unroll") for (int _i = 0; _i < 2; ++_i) \
;         __builtin_amdgcn_global_load_lds((const unsigned*)((const char*)(gbase) + (voff)[_i]), (PG8_LAS unsigned*)(lds + (bufoff) + ldsw + _i * 8192), 16, 0, 0); } while (0)
; #define PG8_LDA(dst, b, h) do { _Pragma("unroll") for (int m = 0; m < 4; ++m) _Pragma("unroll") for (int k = 0; k < 2; ++k) dst[m][k] = *(const PG8_LAS bf16x8*)(lds + PG8_SA(b, h) + aoff + m * 2048 + k * 1024); } while (0)
; #define PG8_MMA(ai, bj, At, Bt) do { __builtin_amdgcn_s_setprio(1); _Pragma("unroll") for (int m = 0; m < 4; ++m) _Pragma("unroll") for (int n = 0; n < 2; ++n) _Pragma("unroll") for (int k = 0; k < 2; ++k) \
;         acc[ai][bj][m][n] = __builtin_amdgcn_mfma_f32_16x16x32_bf16(Bt[n][k], At[m][k], acc[ai][bj][m][n], 0, 0, 0); __builtin_amdgcn_s_setprio(0); } while (0)
; #define PG8_WAIT_V(n) asm volatile("s_waitcnt vmcnt(" #n ")" ::: "memory")
; #define PG8_WAIT_L(n) asm volatile("s_waitcnt lgkmcnt(" #n ")" ::: "memory")
; #define PG8_BAR __builtin_amdgcn_s_barrier()
; #define PG8_SCHED __builtin_amdgcn_sched_barrier(0)
; template <class Epi, class Sched, bool ALIGN_EPI = false, bool SP2 = false, bool ABLK = false, bool BBLK = false>
; __device__ __forceinline__ void gemm_phase(PG8_LAS unsigned char* lds, const Gemm g, const Sched& S, const Epi& E) {
;     ...
;         for (int t = 0; t < nt; t += 2) {
;             const bool last = (t == nt - 2);
;             const char* a1 = cA + (size_t)(t + 1) * kstepA;
;             const char* a2 = last ? nA : cA + (size_t)(t + 2) * kstepA; const char* b2 = last ? nB : cB + (size_t)(t + 2) * kstepB;
;     ...
;             PG8_LDA(At, 1, 1); PG8_STAGE(PG8_SB(1, 0), b3, voffB); PG8_STAGE(PG8_SB(1, 1), b3 + hstepB, voffB); PG8_STAGE(PG8_SA(1, 0), a3, voffA);
;             PG8_WAIT_V(8); PG8_WAIT_L(0); PG8_BAR; PG8_MMA(1, 0, At, B0); PG8_MMA(1, 1, At, B1); PG8_BAR; PG8_SCHED;
;     ...
;         if constexpr (ALIGN_EPI) { if (wr == 0) PG8_BAR; }
	s_add_u32 s26, s24, 0x8000
	s_addc_u32 s27, s25, 0
	s_add_i32 s13, s13, s31
	s_mov_b32 m0, s13
	ds_read_b128 v[186:189], v161 offset:49152
	ds_read_b128 v[190:193], v161 offset:50176
	ds_read_b128 v[194:197], v161 offset:51200
	ds_read_b128 v[198:201], v161 offset:52224
	ds_read_b128 v[202:205], v161 offset:53248
	ds_read_b128 v[206:209], v161 offset:54272
	ds_read_b128 v[210:213], v161 offset:55296
	ds_read_b128 v[214:217], v161 offset:56320
	global_load_lds_dwordx4 v140, s[26:27]
	s_add_i32 m0, s13, 0x2000
	s_add_u32 s24, s24, 0xc000
	s_addc_u32 s25, s25, 0
	s_add_i32 s13, s68, s31
	global_load_lds_dwordx4 v136, s[26:27]
	s_mov_b32 m0, s13
	s_nop 0
	global_load_lds_dwordx4 v140, s[24:25]
	s_add_i32 m0, s13, 0x2000
	s_nop 0
	global_load_lds_dwordx4 v136, s[24:25]
	s_mov_b32 m0, s62
	s_nop 0
	global_load_lds_dwordx4 v142, s[22:23]
	s_mov_b32 m0, s63
	s_nop 0
	global_load_lds_dwordx4 v138, s[22:23]
	s_waitcnt vmcnt(8)
	s_waitcnt lgkmcnt(0)
	v_mfma_f32_16x16x32_bf16 v[68:71], v[152:155], v[186:189], v[68:71]
	v_mfma_f32_16x16x32_bf16 v[64:67], v[162:165], v[186:189], v[64:67]
	v_mfma_f32_16x16x32_bf16 v[52:55], v[152:155], v[194:197], v[52:55]
	v_mfma_f32_16x16x32_bf16 v[48:51], v[162:165], v[194:197], v[48:51]
	s_barrier
	s_setprio 1
	v_mfma_f32_16x16x32_bf16 v[32:35], v[152:155], v[202:205], v[32:35]
	v_mfma_f32_16x16x32_bf16 v[28:31], v[162:165], v[202:205], v[28:31]
	v_mfma_f32_16x16x32_bf16 v[16:19], v[152:155], v[210:213], v[16:19]
	v_mfma_f32_16x16x32_bf16 v[12:15], v[162:165], v[210:213], v[12:15]
	v_mfma_f32_16x16x32_bf16 v[68:71], v[156:159], v[190:193], v[68:71]
	v_mfma_f32_16x16x32_bf16 v[64:67], v[166:169], v[190:193], v[64:67]
	v_mfma_f32_16x16x32_bf16 v[52:55], v[156:159], v[198:201], v[52:55]
	v_mfma_f32_16x16x32_bf16 v[48:51], v[166:169], v[198:201], v[48:51]
	v_mfma_f32_16x16x32_bf16 v[32:35], v[156:159], v[206:209], v[32:35]
	v_mfma_f32_16x16x32_bf16 v[28:31], v[166:169], v[206:209], v[28:31]
	v_mfma_f32_16x16x32_bf16 v[16:19], v[156:159], v[214:217], v[16:19]
	v_mfma_f32_16x16x32_bf16 v[12:15], v[166:169], v[214:217], v[12:15]
	v_mfma_f32_16x16x32_bf16 v[60:63], v[170:173], v[186:189], v[60:63]
	v_mfma_f32_16x16x32_bf16 v[56:59], v[178:181], v[186:189], v[56:59]
	v_mfma_f32_16x16x32_bf16 v[44:47], v[170:173], v[194:197], v[44:47]
	v_mfma_f32_16x16x32_bf16 v[40:43], v[178:181], v[194:197], v[40:43]
	v_mfma_f32_16x16x32_bf16 v[24:27], v[170:173], v[202:205], v[24:27]
	v_mfma_f32_16x16x32_bf16 v[20:23], v[178:181], v[202:205], v[20:23]
	v_mfma_f32_16x16x32_bf16 v[8:11], v[170:173], v[210:213], v[8:11]
	v_mfma_f32_16x16x32_bf16 v[4:7], v[178:181], v[210:213], v[4:7]
	v_mfma_f32_16x16x32_bf16 v[60:63], v[174:177], v[190:193], v[60:63]
	v_mfma_f32_16x16x32_bf16 v[56:59], v[182:185], v[190:193], v[56:59]
	v_mfma_f32_16x16x32_bf16 v[44:47], v[174:177], v[198:201], v[44:47]
	v_mfma_f32_16x16x32_bf16 v[40:43], v[182:185], v[198:201], v[40:43]
	v_mfma_f32_16x16x32_bf16 v[24:27], v[174:177], v[206:209], v[24:27]
	v_mfma_f32_16x16x32_bf16 v[20:23], v[182:185], v[206:209], v[20:23]
	v_mfma_f32_16x16x32_bf16 v[8:11], v[174:177], v[214:217], v[8:11]
	v_mfma_f32_16x16x32_bf16 v[4:7], v[182:185], v[214:217], v[4:7]
	s_setprio 0
	s_barrier
	s_add_i32 vcc_hi, vcc_hi, 2
	s_add_u32 s20, s20, 0x10000
	s_addc_u32 s21, s21, 0
	s_add_u32 s77, s77, 0x10000
	s_addc_u32 vcc_lo, vcc_lo, 0
	s_cmp_gt_u32 vcc_hi, 29
	s_cbranch_scc0 .LBB0_185
	s_and_b64 vcc, exec, s[4:5]
	s_cbranch_vccz .LBB0_188
	s_barrier

; #define PG8_STAGE(bufoff, gbase, voff) do { _Pragma("unroll") for (int _i = 0; _i < 2; ++_i) \
;         __builtin_amdgcn_global_load_lds((const unsigned*)((const char*)(gbase) + (voff)[_i]), (PG8_LAS unsigned*)(lds + (bufoff) + ldsw + _i * 8192), 16, 0, 0); } while (0)
; #define PG8_LDA(dst, b, h) do { _Pragma("unroll") for (int m = 0; m < 4; ++m) _Pragma("unroll") for (int k = 0; k < 2; ++k) dst[m][k] = *(const PG8_LAS bf16x8*)(lds + PG8_SA(b, h) + aoff + m * 2048 + k * 1024); } while (0)
; #define PG8_WAIT_V(n) asm volatile("s_waitcnt vmcnt(" #n ")" ::: "memory")
; #define PG8_WAIT_L(n) asm volatile("s_waitcnt lgkmcnt(" #n ")" ::: "memory")
; template <class Epi, class Sched, bool ALIGN_EPI = false, bool SP2 = false, bool ABLK = false, bool BBLK = false>
; __device__ __forceinline__ void gemm_phase(PG8_LAS unsigned char* lds, const Gemm g, const Sched& S, const Epi& E) {
;     ...
;         for (int t = 0; t < nt; t += 2) {
;             const bool last = (t == nt - 2);
;             const char* a1 = cA + (size_t)(t + 1) * kstepA;
;             const char* a2 = last ? nA : cA + (size_t)(t + 2) * kstepA; const char* b2 = last ? nB : cB + (size_t)(t + 2) * kstepB;
;             const char* a3 = a2 + kstepA; const char* b3 = b2 + kstepB;
;             if (last && has_next) S.a_ready(nxt);
;             if constexpr (SP2) {
;             PG8_LDB(B0, 0, 0); PG8_LDB(B1, 0, 1); PG8_SCHED; PG8_LDA(At, 0, 0); PG8_STAGE(PG8_SA(1, 1), a1 + hstepA, voffA);
;             PG8_WAIT_V(8); PG8_WAIT_L(0); PG8_BAR; PG8_MMA(0, 0, At, B0); PG8_MMA(0, 1, At, B1); PG8_BAR; PG8_SCHED;
;             PG8_LDA(At, 0, 1); PG8_STAGE(PG8_SB(0, 0), b2, voffB); PG8_STAGE(PG8_SB(0, 1), b2 + hstepB, voffB); PG8_STAGE(PG8_SA(0, 0), a2, voffA);
;             PG8_WAIT_V(8); PG8_WAIT_L(0); PG8_BAR; PG8_MMA(1, 0, At, B0); PG8_MMA(1, 1, At, B1); PG8_BAR; PG8_SCHED;
;             PG8_LDB(B0, 1, 0); PG8_LDB(B1, 1, 1); PG8_SCHED; PG8_LDA(At, 1, 0); PG8_STAGE(PG8_SA(0, 1), a2 + hstepA, voffA);
;             PG8_WAIT_V(8); PG8_WAIT_L(0); PG8_BAR; PG8_MMA(0, 0, At, B0); PG8_MMA(0, 1, At, B1); PG8_BAR; PG8_SCHED;
;             PG8_LDA(At, 1, 1); PG8_STAGE(PG8_SB(1, 0), b3, voffB); PG8_STAGE(PG8_SB(1, 1), b3 + hstepB, voffB); PG8_STAGE(PG8_SA(1, 0), a3, voffA);
;             PG8_WAIT_V(8); PG8_WAIT_L(0); PG8_BAR; PG8_MMA(1, 0, At, B0); PG8_MMA(1, 1, At, B1); PG8_BAR; PG8_SCHED;
.LBB0_439:
	s_add_u32 s16, s10, 0x4000
	s_addc_u32 s17, s11, 0
	s_cmpk_eq_i32 s13, 0x54
	s_cselect_b32 s20, s0, s16
	s_cselect_b32 s21, s1, s17
	s_cselect_b32 s18, s8, vcc_lo
	s_cselect_b32 s19, s9, vcc_hi
	s_add_u32 s16, s20, 0x8000
	s_addc_u32 s17, s21, 0
	s_add_i32 s68, 0, 0x10000
	v_add_u32_e32 v36, s68, v148
	s_add_i32 s88, 0, 0x14000
	ds_read_b128 v[152:155], v36
	ds_read_b128 v[156:159], v36 offset:1024
	ds_read_b128 v[160:163], v36 offset:2048
	ds_read_b128 v[164:167], v36 offset:3072
	v_add_u32_e32 v36, s88, v148
	ds_read_b128 v[168:171], v36
	ds_read_b128 v[172:175], v36 offset:1024
	ds_read_b128 v[176:179], v36 offset:2048
	ds_read_b128 v[180:183], v36 offset:3072
	s_add_i32 m0, s27, 0xc000
	ds_read_b128 v[184:187], v150
	ds_read_b128 v[188:191], v150 offset:1024
	ds_read_b128 v[192:195], v150 offset:2048
	ds_read_b128 v[196:199], v150 offset:3072
	ds_read_b128 v[200:203], v150 offset:4096
	ds_read_b128 v[204:207], v150 offset:5120
	ds_read_b128 v[208:211], v150 offset:6144
	ds_read_b128 v[212:215], v150 offset:7168
	global_load_lds_dwordx4 v144, s[10:11]
	s_add_i32 m0, s27, 0xe000
	s_nop 0
	global_load_lds_dwordx4 v146, s[10:11]
	s_waitcnt vmcnt(8)
	s_waitcnt lgkmcnt(0)
	v_mfma_f32_16x16x32_bf16 v[132:135], v[152:155], v[184:187], v[132:135]
	v_mfma_f32_16x16x32_bf16 v[128:131], v[160:163], v[184:187], v[128:131]
	v_mfma_f32_16x16x32_bf16 v[124:127], v[152:155], v[192:195], v[124:127]
	v_mfma_f32_16x16x32_bf16 v[120:123], v[160:163], v[192:195], v[120:123]
	s_barrier
	s_setprio 1
	v_mfma_f32_16x16x32_bf16 v[108:111], v[152:155], v[200:203], v[108:111]
	v_mfma_f32_16x16x32_bf16 v[104:107], v[160:163], v[200:203], v[104:107]
	v_mfma_f32_16x16x32_bf16 v[92:95], v[152:155], v[208:211], v[92:95]
	v_mfma_f32_16x16x32_bf16 v[88:91], v[160:163], v[208:211], v[88:91]
	v_mfma_f32_16x16x32_bf16 v[132:135], v[156:159], v[188:191], v[132:135]
	v_mfma_f32_16x16x32_bf16 v[128:131], v[164:167], v[188:191], v[128:131]
	v_mfma_f32_16x16x32_bf16 v[124:127], v[156:159], v[196:199], v[124:127]
	v_mfma_f32_16x16x32_bf16 v[120:123], v[164:167], v[196:199], v[120:123]
	v_mfma_f32_16x16x32_bf16 v[108:111], v[156:159], v[204:207], v[108:111]
	v_mfma_f32_16x16x32_bf16 v[104:107], v[164:167], v[204:207], v[104:107]
	v_mfma_f32_16x16x32_bf16 v[92:95], v[156:159], v[212:215], v[92:95]
	v_mfma_f32_16x16x32_bf16 v[88:91], v[164:167], v[212:215], v[88:91]
	v_mfma_f32_16x16x32_bf16 v[116:119], v[168:171], v[184:187], v[116:119]
	v_mfma_f32_16x16x32_bf16 v[112:115], v[176:179], v[184:187], v[112:115]
	v_mfma_f32_16x16x32_bf16 v[100:103], v[168:171], v[192:195], v[100:103]
	v_mfma_f32_16x16x32_bf16 v[96:99], v[176:179], v[192:195], v[96:99]
	v_mfma_f32_16x16x32_bf16 v[84:87], v[168:171], v[200:203], v[84:87]
	v_mfma_f32_16x16x32_bf16 v[80:83], v[176:179], v[200:203], v[80:83]
	v_mfma_f32_16x16x32_bf16 v[76:79], v[168:171], v[208:211], v[76:79]
	v_mfma_f32_16x16x32_bf16 v[72:75], v[176:179], v[208:211], v[72:75]
	v_mfma_f32_16x16x32_bf16 v[116:119], v[172:175], v[188:191], v[116:119]
	v_mfma_f32_16x16x32_bf16 v[112:115], v[180:183], v[188:191], v[112:115]
	v_mfma_f32_16x16x32_bf16 v[100:103], v[172:175], v[196:199], v[100:103]
	v_mfma_f32_16x16x32_bf16 v[96:99], v[180:183], v[196:199], v[96:99]
	v_mfma_f32_16x16x32_bf16 v[84:87], v[172:175], v[204:207], v[84:87]
	v_mfma_f32_16x16x32_bf16 v[80:83], v[180:183], v[204:207], v[80:83]
	v_mfma_f32_16x16x32_bf16 v[76:79], v[172:175], v[212:215], v[76:79]
	v_mfma_f32_16x16x32_bf16 v[72:75], v[180:183], v[212:215], v[72:75]
	s_setprio 0
	s_barrier
	s_add_i32 s68, s68, s24
	s_mov_b32 m0, s68
	ds_read_b128 v[184:187], v150 offset:16384
	ds_read_b128 v[188:191], v150 offset:17408
	ds_read_b128 v[192:195], v150 offset:18432
	ds_read_b128 v[196:199], v150 offset:19456
	ds_read_b128 v[200:203], v150 offset:20480
	ds_read_b128 v[204:207], v150 offset:21504
	ds_read_b128 v[208:211], v150 offset:22528
	ds_read_b128 v[212:215], v150 offset:23552
	global_load_lds_dwordx4 v138, s[18:19]
	s_add_i32 m0, s68, 0x2000
	s_add_u32 s68, s18, 0x4000
	s_addc_u32 s69, s19, 0
	s_add_i32 s88, s88, s24
	global_load_lds_dwordx4 v142, s[18:19]
	s_mov_b32 m0, s88
	s_nop 0
	global_load_lds_dwordx4 v138, s[68:69]
	s_add_i32 m0, s88, 0x2000
	s_nop 0
	global_load_lds_dwordx4 v142, s[68:69]
	s_mov_b32 m0, s27
	s_nop 0
	global_load_lds_dwordx4 v136, s[20:21]
	s_mov_b32 m0, s28
	s_nop 0
	global_load_lds_dwordx4 v140, s[20:21]
	s_waitcnt vmcnt(8)
	s_waitcnt lgkmcnt(0)
	v_mfma_f32_16x16x32_bf16 v[68:71], v[152:155], v[184:187], v[68:71]
	v_mfma_f32_16x16x32_bf16 v[64:67], v[160:163], v[184:187], v[64:67]
	v_mfma_f32_16x16x32_bf16 v[60:63], v[152:155], v[192:195], v[60:63]
	v_mfma_f32_16x16x32_bf16 v[56:59], v[160:163], v[192:195], v[56:59]
	s_barrier
; #define PG8_STAGE(bufoff, gbase, voff) do { _Pragma("unroll") for (int _i = 0; _i < 2; ++_i) \
;         __builtin_amdgcn_global_load_lds((const unsigned*)((const char*)(gbase) + (voff)[_i]), (PG8_LAS unsigned*)(lds + (bufoff) + ldsw + _i * 8192), 16, 0, 0); } while (0)
; #define PG8_LDA(dst, b, h) do { _Pragma("unroll") for (int m = 0; m < 4; ++m) _Pragma("unroll") for (int k = 0; k < 2; ++k) dst[m][k] = *(const PG8_LAS bf16x8*)(lds + PG8_SA(b, h) + aoff + m * 2048 + k * 1024); } while (0)
; #define PG8_LDB(dst, b, h) do { _Pragma("unroll") for (int n = 0; n < 2; ++n) _Pragma("unroll") for (int k = 0; k < 2; ++k) dst[n][k] = *(const PG8_LAS bf16x8*)(lds + PG8_SB(b, h) + boff + n * 2048 + k * 1024); } while (0)
; #define PG8_MMA(ai, bj, At, Bt) do { __builtin_amdgcn_s_setprio(1); _Pragma("unroll") for (int m = 0; m < 4; ++m) _Pragma("unroll") for (int n = 0; n < 2; ++n) _Pragma("unroll") for (int k = 0; k < 2; ++k) \
;         acc[ai][bj][m][n] = __builtin_amdgcn_mfma_f32_16x16x32_bf16(Bt[n][k], At[m][k], acc[ai][bj][m][n], 0, 0, 0); __builtin_amdgcn_s_setprio(0); } while (0)
; template <class Epi, class Sched, bool ALIGN_EPI = false, bool SP2 = false, bool ABLK = false, bool BBLK = false>
; __device__ __forceinline__ void gemm_phase(PG8_LAS unsigned char* lds, const Gemm g, const Sched& S, const Epi& E) {
;     ...
;             PG8_LDB(B0, 0, 0); PG8_LDB(B1, 0, 1); PG8_SCHED; PG8_LDA(At, 0, 0); PG8_STAGE(PG8_SA(1, 1), a1 + hstepA, voffA);
;             PG8_WAIT_V(8); PG8_WAIT_L(0); PG8_BAR; PG8_MMA(0, 0, At, B0); PG8_MMA(0, 1, At, B1); PG8_BAR; PG8_SCHED;
;             PG8_LDA(At, 0, 1); PG8_STAGE(PG8_SB(0, 0), b2, voffB); PG8_STAGE(PG8_SB(0, 1), b2 + hstepB, voffB); PG8_STAGE(PG8_SA(0, 0), a2, voffA);
;             PG8_WAIT_V(8); PG8_WAIT_L(0); PG8_BAR; PG8_MMA(1, 0, At, B0); PG8_MMA(1, 1, At, B1); PG8_BAR; PG8_SCHED;
;             PG8_LDB(B0, 1, 0); PG8_LDB(B1, 1, 1); PG8_SCHED; PG8_LDA(At, 1, 0); PG8_STAGE(PG8_SA(0, 1), a2 + hstepA, voffA);
;             PG8_WAIT_V(8); PG8_WAIT_L(0); PG8_BAR; PG8_MMA(0, 0, At, B0); PG8_MMA(0, 1, At, B1); PG8_BAR; PG8_SCHED;
;             PG8_LDA(At, 1, 1); PG8_STAGE(PG8_SB(1, 0), b3, voffB); PG8_STAGE(PG8_SB(1, 1), b3 + hstepB, voffB); PG8_STAGE(PG8_SA(1, 0), a3, voffA);
;             PG8_WAIT_V(8); PG8_WAIT_L(0); PG8_BAR; PG8_MMA(1, 0, At, B0); PG8_MMA(1, 1, At, B1); PG8_BAR; PG8_SCHED;
	s_setprio 1
	v_mfma_f32_16x16x32_bf16 v[44:47], v[152:155], v[200:203], v[44:47]
	v_mfma_f32_16x16x32_bf16 v[40:43], v[160:163], v[200:203], v[40:43]
	v_mfma_f32_16x16x32_bf16 v[24:27], v[152:155], v[208:211], v[24:27]
	v_mfma_f32_16x16x32_bf16 v[20:23], v[160:163], v[208:211], v[20:23]
	v_mfma_f32_16x16x32_bf16 v[68:71], v[156:159], v[188:191], v[68:71]
	v_mfma_f32_16x16x32_bf16 v[64:67], v[164:167], v[188:191], v[64:67]
	v_mfma_f32_16x16x32_bf16 v[60:63], v[156:159], v[196:199], v[60:63]
	v_mfma_f32_16x16x32_bf16 v[56:59], v[164:167], v[196:199], v[56:59]
	v_mfma_f32_16x16x32_bf16 v[44:47], v[156:159], v[204:207], v[44:47]
	v_mfma_f32_16x16x32_bf16 v[40:43], v[164:167], v[204:207], v[40:43]
	v_mfma_f32_16x16x32_bf16 v[24:27], v[156:159], v[212:215], v[24:27]
	v_mfma_f32_16x16x32_bf16 v[20:23], v[164:167], v[212:215], v[20:23]
	v_mfma_f32_16x16x32_bf16 v[52:55], v[168:171], v[184:187], v[52:55]
	v_mfma_f32_16x16x32_bf16 v[48:51], v[176:179], v[184:187], v[48:51]
	v_mfma_f32_16x16x32_bf16 v[32:35], v[168:171], v[192:195], v[32:35]
	v_mfma_f32_16x16x32_bf16 v[28:31], v[176:179], v[192:195], v[28:31]
	v_mfma_f32_16x16x32_bf16 v[16:19], v[168:171], v[200:203], v[16:19]
	v_mfma_f32_16x16x32_bf16 v[12:15], v[176:179], v[200:203], v[12:15]
	v_mfma_f32_16x16x32_bf16 v[8:11], v[168:171], v[208:211], v[8:11]
	v_mfma_f32_16x16x32_bf16 v[4:7], v[176:179], v[208:211], v[4:7]
	v_mfma_f32_16x16x32_bf16 v[52:55], v[172:175], v[188:191], v[52:55]
	v_mfma_f32_16x16x32_bf16 v[48:51], v[180:183], v[188:191], v[48:51]
	v_mfma_f32_16x16x32_bf16 v[32:35], v[172:175], v[196:199], v[32:35]
	v_mfma_f32_16x16x32_bf16 v[28:31], v[180:183], v[196:199], v[28:31]
	v_mfma_f32_16x16x32_bf16 v[16:19], v[172:175], v[204:207], v[16:19]
	v_mfma_f32_16x16x32_bf16 v[12:15], v[180:183], v[204:207], v[12:15]
	v_mfma_f32_16x16x32_bf16 v[8:11], v[172:175], v[212:215], v[8:11]
	v_mfma_f32_16x16x32_bf16 v[4:7], v[180:183], v[212:215], v[4:7]
	s_setprio 0
	s_barrier
	s_add_i32 s68, 0, 0x18000
	v_add_u32_e32 v36, s68, v148
	s_add_i32 s69, 0, 0x1c000
	ds_read_b128 v[152:155], v36
	ds_read_b128 v[156:159], v36 offset:1024
	ds_read_b128 v[160:163], v36 offset:2048
	ds_read_b128 v[164:167], v36 offset:3072
	v_add_u32_e32 v36, s69, v148
	ds_read_b128 v[168:171], v36
	ds_read_b128 v[172:175], v36 offset:1024
	ds_read_b128 v[176:179], v36 offset:2048
	ds_read_b128 v[180:183], v36 offset:3072
	s_add_u32 s20, s20, 0x4000
	s_addc_u32 s21, s21, 0
	s_mov_b32 m0, s29
	ds_read_b128 v[184:187], v150 offset:32768
	ds_read_b128 v[188:191], v150 offset:33792
	ds_read_b128 v[192:195], v150 offset:34816
	ds_read_b128 v[196:199], v150 offset:35840
	ds_read_b128 v[200:203], v150 offset:36864
	ds_read_b128 v[204:207], v150 offset:37888
	ds_read_b128 v[208:211], v150 offset:38912
	ds_read_b128 v[212:215], v150 offset:39936
	global_load_lds_dwordx4 v136, s[20:21]
	s_mov_b32 m0, s30
	s_nop 0
	global_load_lds_dwordx4 v140, s[20:21]
	s_waitcnt vmcnt(8)
	s_waitcnt lgkmcnt(0)
	v_mfma_f32_16x16x32_bf16 v[132:135], v[152:155], v[184:187], v[132:135]
	v_mfma_f32_16x16x32_bf16 v[128:131], v[160:163], v[184:187], v[128:131]
	v_mfma_f32_16x16x32_bf16 v[124:127], v[152:155], v[192:195], v[124:127]
	v_mfma_f32_16x16x32_bf16 v[120:123], v[160:163], v[192:195], v[120:123]
	s_barrier
	s_setprio 1
	v_mfma_f32_16x16x32_bf16 v[108:111], v[152:155], v[200:203], v[108:111]
	v_mfma_f32_16x16x32_bf16 v[104:107], v[160:163], v[200:203], v[104:107]
	v_mfma_f32_16x16x32_bf16 v[92:95], v[152:155], v[208:211], v[92:95]
	v_mfma_f32_16x16x32_bf16 v[88:91], v[160:163], v[208:211], v[88:91]
	v_mfma_f32_16x16x32_bf16 v[132:135], v[156:159], v[188:191], v[132:135]
	v_mfma_f32_16x16x32_bf16 v[128:131], v[164:167], v[188:191], v[128:131]
	v_mfma_f32_16x16x32_bf16 v[124:127], v[156:159], v[196:199], v[124:127]
	v_mfma_f32_16x16x32_bf16 v[120:123], v[164:167], v[196:199], v[120:123]
	v_mfma_f32_16x16x32_bf16 v[108:111], v[156:159], v[204:207], v[108:111]
	v_mfma_f32_16x16x32_bf16 v[104:107], v[164:167], v[204:207], v[104:107]
	v_mfma_f32_16x16x32_bf16 v[92:95], v[156:159], v[212:215], v[92:95]
	v_mfma_f32_16x16x32_bf16 v[88:91], v[164:167], v[212:215], v[88:91]
	v_mfma_f32_16x16x32_bf16 v[116:119], v[168:171], v[184:187], v[116:119]
	v_mfma_f32_16x16x32_bf16 v[112:115], v[176:179], v[184:187], v[112:115]
	v_mfma_f32_16x16x32_bf16 v[100:103], v[168:171], v[192:195], v[100:103]
	v_mfma_f32_16x16x32_bf16 v[96:99], v[176:179], v[192:195], v[96:99]
	v_mfma_f32_16x16x32_bf16 v[84:87], v[168:171], v[200:203], v[84:87]
	v_mfma_f32_16x16x32_bf16 v[80:83], v[176:179], v[200:203], v[80:83]
	v_mfma_f32_16x16x32_bf16 v[76:79], v[168:171], v[208:211], v[76:79]
	v_mfma_f32_16x16x32_bf16 v[72:75], v[176:179], v[208:211], v[72:75]
	v_mfma_f32_16x16x32_bf16 v[116:119], v[172:175], v[188:191], v[116:119]
	v_mfma_f32_16x16x32_bf16 v[112:115], v[180:183], v[188:191], v[112:115]
	v_mfma_f32_16x16x32_bf16 v[100:103], v[172:175], v[196:199], v[100:103]
	v_mfma_f32_16x16x32_bf16 v[96:99], v[180:183], v[196:199], v[96:99]
	v_mfma_f32_16x16x32_bf16 v[84:87], v[172:175], v[204:207], v[84:87]
	v_mfma_f32_16x16x32_bf16 v[80:83], v[180:183], v[204:207], v[80:83]
	v_mfma_f32_16x16x32_bf16 v[76:79], v[172:175], v[212:215], v[76:79]
	v_mfma_f32_16x16x32_bf16 v[72:75], v[180:183], v[212:215], v[72:75]
	s_setprio 0
	s_barrier
; #define PG8_STAGE(bufoff, gbase, voff) do { _Pragma("unroll") for (int _i = 0; _i < 2; ++_i) \
;         __builtin_amdgcn_global_load_lds((const unsigned*)((const char*)(gbase) + (voff)[_i]), (PG8_LAS unsigned*)(lds + (bufoff) + ldsw + _i * 8192), 16, 0, 0); } while (0)
; #define PG8_LDA(dst, b, h) do { _Pragma("unroll") for (int m = 0; m < 4; ++m) _Pragma("unroll") for (int k = 0; k < 2; ++k) dst[m][k] = *(const PG8_LAS bf16x8*)(lds + PG8_SA(b, h) + aoff + m * 2048 + k * 1024); } while (0)
; #define PG8_MMA(ai, bj, At, Bt) do { __builtin_amdgcn_s_setprio(1); _Pragma("unroll") for (int m = 0; m < 4; ++m) _Pragma("unroll") for (int n = 0; n < 2; ++n) _Pragma("unroll") for (int k = 0; k < 2; ++k) \
;         acc[ai][bj][m][n] = __builtin_amdgcn_mfma_f32_16x16x32_bf16(Bt[n][k], At[m][k], acc[ai][bj][m][n], 0, 0, 0); __builtin_amdgcn_s_setprio(0); } while (0)
; #define PG8_WAIT_V(n) asm volatile("s_waitcnt vmcnt(" #n ")" ::: "memory")
; #define PG8_WAIT_L(n) asm volatile("s_waitcnt lgkmcnt(" #n ")" ::: "memory")
; #define PG8_BAR __builtin_amdgcn_s_barrier()
; #define PG8_SCHED __builtin_amdgcn_sched_barrier(0)
; template <class Epi, class Sched, bool ALIGN_EPI = false, bool SP2 = false, bool ABLK = false, bool BBLK = false>
; __device__ __forceinline__ void gemm_phase(PG8_LAS unsigned char* lds, const Gemm g, const Sched& S, const Epi& E) {
;     ...
;         for (int t = 0; t < nt; t += 2) {
;             const bool last = (t == nt - 2);
;             const char* a1 = cA + (size_t)(t + 1) * kstepA;
;             const char* a2 = last ? nA : cA + (size_t)(t + 2) * kstepA; const char* b2 = last ? nB : cB + (size_t)(t + 2) * kstepB;
;     ...
;             PG8_LDA(At, 1, 1); PG8_STAGE(PG8_SB(1, 0), b3, voffB); PG8_STAGE(PG8_SB(1, 1), b3 + hstepB, voffB); PG8_STAGE(PG8_SA(1, 0), a3, voffA);
;             PG8_WAIT_V(8); PG8_WAIT_L(0); PG8_BAR; PG8_MMA(1, 0, At, B0); PG8_MMA(1, 1, At, B1); PG8_BAR; PG8_SCHED;
;     ...
;         if constexpr (ALIGN_EPI) { if (wr == 0) PG8_BAR; }
	s_add_u32 s20, s18, 0x8000
	s_addc_u32 s21, s19, 0
	s_add_i32 s68, s68, s24
	s_mov_b32 m0, s68
	ds_read_b128 v[184:187], v150 offset:49152
	ds_read_b128 v[188:191], v150 offset:50176
	ds_read_b128 v[192:195], v150 offset:51200
	ds_read_b128 v[196:199], v150 offset:52224
	ds_read_b128 v[200:203], v150 offset:53248
	ds_read_b128 v[204:207], v150 offset:54272
	ds_read_b128 v[208:211], v150 offset:55296
	ds_read_b128 v[212:215], v150 offset:56320
	global_load_lds_dwordx4 v138, s[20:21]
	s_add_i32 m0, s68, 0x2000
	s_add_u32 s18, s18, 0xc000
	s_addc_u32 s19, s19, 0
	global_load_lds_dwordx4 v142, s[20:21]
	s_add_i32 s20, s69, s24
	s_mov_b32 m0, s20
	s_nop 0
	global_load_lds_dwordx4 v138, s[18:19]
	s_add_i32 m0, s20, 0x2000
	s_nop 0
	global_load_lds_dwordx4 v142, s[18:19]
	s_mov_b32 m0, s35
	s_nop 0
	global_load_lds_dwordx4 v136, s[16:17]
	s_mov_b32 m0, s70
	s_nop 0
	global_load_lds_dwordx4 v140, s[16:17]
	s_waitcnt vmcnt(8)
	s_waitcnt lgkmcnt(0)
	v_mfma_f32_16x16x32_bf16 v[68:71], v[152:155], v[184:187], v[68:71]
	v_mfma_f32_16x16x32_bf16 v[64:67], v[160:163], v[184:187], v[64:67]
	v_mfma_f32_16x16x32_bf16 v[60:63], v[152:155], v[192:195], v[60:63]
	v_mfma_f32_16x16x32_bf16 v[56:59], v[160:163], v[192:195], v[56:59]
	s_barrier
	s_setprio 1
	v_mfma_f32_16x16x32_bf16 v[44:47], v[152:155], v[200:203], v[44:47]
	v_mfma_f32_16x16x32_bf16 v[40:43], v[160:163], v[200:203], v[40:43]
	v_mfma_f32_16x16x32_bf16 v[24:27], v[152:155], v[208:211], v[24:27]
	v_mfma_f32_16x16x32_bf16 v[20:23], v[160:163], v[208:211], v[20:23]
	v_mfma_f32_16x16x32_bf16 v[68:71], v[156:159], v[188:191], v[68:71]
	v_mfma_f32_16x16x32_bf16 v[64:67], v[164:167], v[188:191], v[64:67]
	v_mfma_f32_16x16x32_bf16 v[60:63], v[156:159], v[196:199], v[60:63]
	v_mfma_f32_16x16x32_bf16 v[56:59], v[164:167], v[196:199], v[56:59]
	v_mfma_f32_16x16x32_bf16 v[44:47], v[156:159], v[204:207], v[44:47]
	v_mfma_f32_16x16x32_bf16 v[40:43], v[164:167], v[204:207], v[40:43]
	v_mfma_f32_16x16x32_bf16 v[24:27], v[156:159], v[212:215], v[24:27]
	v_mfma_f32_16x16x32_bf16 v[20:23], v[164:167], v[212:215], v[20:23]
	v_mfma_f32_16x16x32_bf16 v[52:55], v[168:171], v[184:187], v[52:55]
	v_mfma_f32_16x16x32_bf16 v[48:51], v[176:179], v[184:187], v[48:51]
	v_mfma_f32_16x16x32_bf16 v[32:35], v[168:171], v[192:195], v[32:35]
	v_mfma_f32_16x16x32_bf16 v[28:31], v[176:179], v[192:195], v[28:31]
	v_mfma_f32_16x16x32_bf16 v[16:19], v[168:171], v[200:203], v[16:19]
	v_mfma_f32_16x16x32_bf16 v[12:15], v[176:179], v[200:203], v[12:15]
	v_mfma_f32_16x16x32_bf16 v[8:11], v[168:171], v[208:211], v[8:11]
	v_mfma_f32_16x16x32_bf16 v[4:7], v[176:179], v[208:211], v[4:7]
	v_mfma_f32_16x16x32_bf16 v[52:55], v[172:175], v[188:191], v[52:55]
	v_mfma_f32_16x16x32_bf16 v[48:51], v[180:183], v[188:191], v[48:51]
	v_mfma_f32_16x16x32_bf16 v[32:35], v[172:175], v[196:199], v[32:35]
	v_mfma_f32_16x16x32_bf16 v[28:31], v[180:183], v[196:199], v[28:31]
	v_mfma_f32_16x16x32_bf16 v[16:19], v[172:175], v[204:207], v[16:19]
	v_mfma_f32_16x16x32_bf16 v[12:15], v[180:183], v[204:207], v[12:15]
	v_mfma_f32_16x16x32_bf16 v[8:11], v[172:175], v[212:215], v[8:11]
	v_mfma_f32_16x16x32_bf16 v[4:7], v[180:183], v[212:215], v[4:7]
	s_setprio 0
	s_barrier
	s_add_i32 s13, s13, 2
	s_add_u32 s10, s10, 0x10000
	s_addc_u32 s11, s11, 0
	s_add_u32 vcc_lo, vcc_lo, 0x10000
	s_addc_u32 vcc_hi, vcc_hi, 0
	s_cmpk_gt_u32 s13, 0x55
	s_cbranch_scc0 .LBB0_439
	s_and_b64 vcc, exec, s[6:7]
	s_cbranch_vccz .LBB0_442
	s_barrier

; #define PG8_STAGE(bufoff, gbase, voff) do { _Pragma("unroll") for (int _i = 0; _i < 2; ++_i) \
;         __builtin_amdgcn_global_load_lds((const unsigned*)((const char*)(gbase) + (voff)[_i]), (PG8_LAS unsigned*)(lds + (bufoff) + ldsw + _i * 8192), 16, 0, 0); } while (0)
; #define PG8_LDA(dst, b, h) do { _Pragma("unroll") for (int m = 0; m < 4; ++m) _Pragma("unroll") for (int k = 0; k < 2; ++k) dst[m][k] = *(const PG8_LAS bf16x8*)(lds + PG8_SA(b, h) + aoff + m * 2048 + k * 1024); } while (0)
; #define PG8_WAIT_V(n) asm volatile("s_waitcnt vmcnt(" #n ")" ::: "memory")
; #define PG8_WAIT_L(n) asm volatile("s_waitcnt lgkmcnt(" #n ")" ::: "memory")
; template <class Epi, class Sched, bool ALIGN_EPI = false, bool SP2 = false, bool ABLK = false, bool BBLK = false>
; __device__ __forceinline__ void gemm_phase(PG8_LAS unsigned char* lds, const Gemm g, const Sched& S, const Epi& E) {
;     ...
;         for (int t = 0; t < nt; t += 2) {
;             const bool last = (t == nt - 2);
;             const char* a1 = cA + (size_t)(t + 1) * kstepA;
;             const char* a2 = last ? nA : cA + (size_t)(t + 2) * kstepA; const char* b2 = last ? nB : cB + (size_t)(t + 2) * kstepB;
;             const char* a3 = a2 + kstepA; const char* b3 = b2 + kstepB;
;             if (last && has_next) S.a_ready(nxt);
;             if constexpr (SP2) {
;             PG8_LDB(B0, 0, 0); PG8_LDB(B1, 0, 1); PG8_SCHED; PG8_LDA(At, 0, 0); PG8_STAGE(PG8_SA(1, 1), a1 + hstepA, voffA);
;             PG8_WAIT_V(8); PG8_WAIT_L(0); PG8_BAR; PG8_MMA(0, 0, At, B0); PG8_MMA(0, 1, At, B1); PG8_BAR; PG8_SCHED;
;             PG8_LDA(At, 0, 1); PG8_STAGE(PG8_SB(0, 0), b2, voffB); PG8_STAGE(PG8_SB(0, 1), b2 + hstepB, voffB); PG8_STAGE(PG8_SA(0, 0), a2, voffA);
;             PG8_WAIT_V(8); PG8_WAIT_L(0); PG8_BAR; PG8_MMA(1, 0, At, B0); PG8_MMA(1, 1, At, B1); PG8_BAR; PG8_SCHED;
;             PG8_LDB(B0, 1, 0); PG8_LDB(B1, 1, 1); PG8_SCHED; PG8_LDA(At, 1, 0); PG8_STAGE(PG8_SA(0, 1), a2 + hstepA, voffA);
;             PG8_WAIT_V(8); PG8_WAIT_L(0); PG8_BAR; PG8_MMA(0, 0, At, B0); PG8_MMA(0, 1, At, B1); PG8_BAR; PG8_SCHED;
;             PG8_LDA(At, 1, 1); PG8_STAGE(PG8_SB(1, 0), b3, voffB); PG8_STAGE(PG8_SB(1, 1), b3 + hstepB, voffB); PG8_STAGE(PG8_SA(1, 0), a3, voffA);
;             PG8_WAIT_V(8); PG8_WAIT_L(0); PG8_BAR; PG8_MMA(1, 0, At, B0); PG8_MMA(1, 1, At, B1); PG8_BAR; PG8_SCHED;
.LBB0_916:
	s_add_u32 s22, s20, 0x4000
	s_addc_u32 s23, s21, 0
	s_cmp_eq_u32 s13, 28
	s_cselect_b32 s26, s19, s22
	s_cselect_b32 s27, s1, s23
	s_cselect_b32 s24, s65, s70
	s_cselect_b32 s25, s9, s71
	s_add_u32 s22, s26, 0x8000
	s_addc_u32 s23, s27, 0
	s_add_i32 s68, 0, 0x10000
	v_add_u32_e32 v36, s68, v155
	s_add_i32 s77, 0, 0x14000
	ds_read_b128 v[150:153], v36
	ds_read_b128 v[158:161], v36 offset:1024
	ds_read_b128 v[162:165], v36 offset:2048
	ds_read_b128 v[166:169], v36 offset:3072
	v_add_u32_e32 v36, s77, v155
	ds_read_b128 v[170:173], v36
	ds_read_b128 v[174:177], v36 offset:1024
	ds_read_b128 v[178:181], v36 offset:2048
	ds_read_b128 v[182:185], v36 offset:3072
	s_add_i32 m0, s31, 0xc000
	ds_read_b128 v[186:189], v157
	ds_read_b128 v[190:193], v157 offset:1024
	ds_read_b128 v[194:197], v157 offset:2048
	ds_read_b128 v[198:201], v157 offset:3072
	ds_read_b128 v[202:205], v157 offset:4096
	ds_read_b128 v[206:209], v157 offset:5120
	ds_read_b128 v[210:213], v157 offset:6144
	ds_read_b128 v[214:217], v157 offset:7168
	global_load_lds_dwordx4 v146, s[20:21]
	s_add_i32 m0, s31, 0xe000
	s_nop 0
	global_load_lds_dwordx4 v148, s[20:21]
	s_waitcnt vmcnt(8)
	s_waitcnt lgkmcnt(0)
	v_mfma_f32_16x16x32_bf16 v[132:135], v[150:153], v[186:189], v[132:135]
	v_mfma_f32_16x16x32_bf16 v[128:131], v[162:165], v[186:189], v[128:131]
	v_mfma_f32_16x16x32_bf16 v[124:127], v[150:153], v[194:197], v[124:127]
	v_mfma_f32_16x16x32_bf16 v[116:119], v[162:165], v[194:197], v[116:119]
	s_barrier
	s_setprio 1
	v_mfma_f32_16x16x32_bf16 v[108:111], v[150:153], v[202:205], v[108:111]
	v_mfma_f32_16x16x32_bf16 v[100:103], v[162:165], v[202:205], v[100:103]
	v_mfma_f32_16x16x32_bf16 v[92:95], v[150:153], v[210:213], v[92:95]
	v_mfma_f32_16x16x32_bf16 v[84:87], v[162:165], v[210:213], v[84:87]
	v_mfma_f32_16x16x32_bf16 v[132:135], v[158:161], v[190:193], v[132:135]
	v_mfma_f32_16x16x32_bf16 v[128:131], v[166:169], v[190:193], v[128:131]
	v_mfma_f32_16x16x32_bf16 v[124:127], v[158:161], v[198:201], v[124:127]
	v_mfma_f32_16x16x32_bf16 v[116:119], v[166:169], v[198:201], v[116:119]
	v_mfma_f32_16x16x32_bf16 v[108:111], v[158:161], v[206:209], v[108:111]
	v_mfma_f32_16x16x32_bf16 v[100:103], v[166:169], v[206:209], v[100:103]
	v_mfma_f32_16x16x32_bf16 v[92:95], v[158:161], v[214:217], v[92:95]
	v_mfma_f32_16x16x32_bf16 v[84:87], v[166:169], v[214:217], v[84:87]
	v_mfma_f32_16x16x32_bf16 v[120:123], v[170:173], v[186:189], v[120:123]
	v_mfma_f32_16x16x32_bf16 v[112:115], v[178:181], v[186:189], v[112:115]
	v_mfma_f32_16x16x32_bf16 v[104:107], v[170:173], v[194:197], v[104:107]
	v_mfma_f32_16x16x32_bf16 v[96:99], v[178:181], v[194:197], v[96:99]
	v_mfma_f32_16x16x32_bf16 v[88:91], v[170:173], v[202:205], v[88:91]
	v_mfma_f32_16x16x32_bf16 v[80:83], v[178:181], v[202:205], v[80:83]
	v_mfma_f32_16x16x32_bf16 v[76:79], v[170:173], v[210:213], v[76:79]
	v_mfma_f32_16x16x32_bf16 v[72:75], v[178:181], v[210:213], v[72:75]
	v_mfma_f32_16x16x32_bf16 v[120:123], v[174:177], v[190:193], v[120:123]
	v_mfma_f32_16x16x32_bf16 v[112:115], v[182:185], v[190:193], v[112:115]
	v_mfma_f32_16x16x32_bf16 v[104:107], v[174:177], v[198:201], v[104:107]
	v_mfma_f32_16x16x32_bf16 v[96:99], v[182:185], v[198:201], v[96:99]
	v_mfma_f32_16x16x32_bf16 v[88:91], v[174:177], v[206:209], v[88:91]
	v_mfma_f32_16x16x32_bf16 v[80:83], v[182:185], v[206:209], v[80:83]
	v_mfma_f32_16x16x32_bf16 v[76:79], v[174:177], v[214:217], v[76:79]
	v_mfma_f32_16x16x32_bf16 v[72:75], v[182:185], v[214:217], v[72:75]
	s_setprio 0
	s_barrier
	s_add_i32 s68, s68, s29
	s_mov_b32 m0, s68
	ds_read_b128 v[186:189], v157 offset:16384
	ds_read_b128 v[190:193], v157 offset:17408
	ds_read_b128 v[194:197], v157 offset:18432
	ds_read_b128 v[198:201], v157 offset:19456
	ds_read_b128 v[202:205], v157 offset:20480
	ds_read_b128 v[206:209], v157 offset:21504
	ds_read_b128 v[210:213], v157 offset:22528
	ds_read_b128 v[214:217], v157 offset:23552
	global_load_lds_dwordx4 v140, s[24:25]
	s_add_i32 m0, s68, 0x2000
	s_add_u32 s68, s24, 0x4000
	s_addc_u32 s69, s25, 0
	s_add_i32 s77, s77, s29
	global_load_lds_dwordx4 v136, s[24:25]
	s_mov_b32 m0, s77
	s_nop 0
	global_load_lds_dwordx4 v140, s[68:69]
	s_add_i32 m0, s77, 0x2000
	s_nop 0
	global_load_lds_dwordx4 v136, s[68:69]
	s_mov_b32 m0, s31
	s_nop 0
	global_load_lds_dwordx4 v142, s[26:27]
	s_mov_b32 m0, s34
	s_nop 0
	global_load_lds_dwordx4 v138, s[26:27]
	s_waitcnt vmcnt(8)
	s_waitcnt lgkmcnt(0)
	v_mfma_f32_16x16x32_bf16 v[68:71], v[150:153], v[186:189], v[68:71]
	v_mfma_f32_16x16x32_bf16 v[64:67], v[162:165], v[186:189], v[64:67]
	v_mfma_f32_16x16x32_bf16 v[60:63], v[150:153], v[194:197], v[60:63]
	v_mfma_f32_16x16x32_bf16 v[52:55], v[162:165], v[194:197], v[52:55]
	s_barrier
; #define PG8_STAGE(bufoff, gbase, voff) do { _Pragma("unroll") for (int _i = 0; _i < 2; ++_i) \
;         __builtin_amdgcn_global_load_lds((const unsigned*)((const char*)(gbase) + (voff)[_i]), (PG8_LAS unsigned*)(lds + (bufoff) + ldsw + _i * 8192), 16, 0, 0); } while (0)
; #define PG8_LDA(dst, b, h) do { _Pragma("unroll") for (int m = 0; m < 4; ++m) _Pragma("unroll") for (int k = 0; k < 2; ++k) dst[m][k] = *(const PG8_LAS bf16x8*)(lds + PG8_SA(b, h) + aoff + m * 2048 + k * 1024); } while (0)
; #define PG8_LDB(dst, b, h) do { _Pragma("unroll") for (int n = 0; n < 2; ++n) _Pragma("unroll") for (int k = 0; k < 2; ++k) dst[n][k] = *(const PG8_LAS bf16x8*)(lds + PG8_SB(b, h) + boff + n * 2048 + k * 1024); } while (0)
; #define PG8_MMA(ai, bj, At, Bt) do { __builtin_amdgcn_s_setprio(1); _Pragma("unroll") for (int m = 0; m < 4; ++m) _Pragma("unroll") for (int n = 0; n < 2; ++n) _Pragma("unroll") for (int k = 0; k < 2; ++k) \
;         acc[ai][bj][m][n] = __builtin_amdgcn_mfma_f32_16x16x32_bf16(Bt[n][k], At[m][k], acc[ai][bj][m][n], 0, 0, 0); __builtin_amdgcn_s_setprio(0); } while (0)
; template <class Epi, class Sched, bool ALIGN_EPI = false, bool SP2 = false, bool ABLK = false, bool BBLK = false>
; __device__ __forceinline__ void gemm_phase(PG8_LAS unsigned char* lds, const Gemm g, const Sched& S, const Epi& E) {
;     ...
;             PG8_LDB(B0, 0, 0); PG8_LDB(B1, 0, 1); PG8_SCHED; PG8_LDA(At, 0, 0); PG8_STAGE(PG8_SA(1, 1), a1 + hstepA, voffA);
;             PG8_WAIT_V(8); PG8_WAIT_L(0); PG8_BAR; PG8_MMA(0, 0, At, B0); PG8_MMA(0, 1, At, B1); PG8_BAR; PG8_SCHED;
;             PG8_LDA(At, 0, 1); PG8_STAGE(PG8_SB(0, 0), b2, voffB); PG8_STAGE(PG8_SB(0, 1), b2 + hstepB, voffB); PG8_STAGE(PG8_SA(0, 0), a2, voffA);
;             PG8_WAIT_V(8); PG8_WAIT_L(0); PG8_BAR; PG8_MMA(1, 0, At, B0); PG8_MMA(1, 1, At, B1); PG8_BAR; PG8_SCHED;
;             PG8_LDB(B0, 1, 0); PG8_LDB(B1, 1, 1); PG8_SCHED; PG8_LDA(At, 1, 0); PG8_STAGE(PG8_SA(0, 1), a2 + hstepA, voffA);
;             PG8_WAIT_V(8); PG8_WAIT_L(0); PG8_BAR; PG8_MMA(0, 0, At, B0); PG8_MMA(0, 1, At, B1); PG8_BAR; PG8_SCHED;
;             PG8_LDA(At, 1, 1); PG8_STAGE(PG8_SB(1, 0), b3, voffB); PG8_STAGE(PG8_SB(1, 1), b3 + hstepB, voffB); PG8_STAGE(PG8_SA(1, 0), a3, voffA);
;             PG8_WAIT_V(8); PG8_WAIT_L(0); PG8_BAR; PG8_MMA(1, 0, At, B0); PG8_MMA(1, 1, At, B1); PG8_BAR; PG8_SCHED;
	s_setprio 1
	v_mfma_f32_16x16x32_bf16 v[44:47], v[150:153], v[202:205], v[44:47]
	v_mfma_f32_16x16x32_bf16 v[32:35], v[162:165], v[202:205], v[32:35]
	v_mfma_f32_16x16x32_bf16 v[24:27], v[150:153], v[210:213], v[24:27]
	v_mfma_f32_16x16x32_bf16 v[16:19], v[162:165], v[210:213], v[16:19]
	v_mfma_f32_16x16x32_bf16 v[68:71], v[158:161], v[190:193], v[68:71]
	v_mfma_f32_16x16x32_bf16 v[64:67], v[166:169], v[190:193], v[64:67]
	v_mfma_f32_16x16x32_bf16 v[60:63], v[158:161], v[198:201], v[60:63]
	v_mfma_f32_16x16x32_bf16 v[52:55], v[166:169], v[198:201], v[52:55]
	v_mfma_f32_16x16x32_bf16 v[44:47], v[158:161], v[206:209], v[44:47]
	v_mfma_f32_16x16x32_bf16 v[32:35], v[166:169], v[206:209], v[32:35]
	v_mfma_f32_16x16x32_bf16 v[24:27], v[158:161], v[214:217], v[24:27]
	v_mfma_f32_16x16x32_bf16 v[16:19], v[166:169], v[214:217], v[16:19]
	v_mfma_f32_16x16x32_bf16 v[56:59], v[170:173], v[186:189], v[56:59]
	v_mfma_f32_16x16x32_bf16 v[48:51], v[178:181], v[186:189], v[48:51]
	v_mfma_f32_16x16x32_bf16 v[40:43], v[170:173], v[194:197], v[40:43]
	v_mfma_f32_16x16x32_bf16 v[28:31], v[178:181], v[194:197], v[28:31]
	v_mfma_f32_16x16x32_bf16 v[20:23], v[170:173], v[202:205], v[20:23]
	v_mfma_f32_16x16x32_bf16 v[12:15], v[178:181], v[202:205], v[12:15]
	v_mfma_f32_16x16x32_bf16 v[8:11], v[170:173], v[210:213], v[8:11]
	v_mfma_f32_16x16x32_bf16 v[4:7], v[178:181], v[210:213], v[4:7]
	v_mfma_f32_16x16x32_bf16 v[56:59], v[174:177], v[190:193], v[56:59]
	v_mfma_f32_16x16x32_bf16 v[48:51], v[182:185], v[190:193], v[48:51]
	v_mfma_f32_16x16x32_bf16 v[40:43], v[174:177], v[198:201], v[40:43]
	v_mfma_f32_16x16x32_bf16 v[28:31], v[182:185], v[198:201], v[28:31]
	v_mfma_f32_16x16x32_bf16 v[20:23], v[174:177], v[206:209], v[20:23]
	v_mfma_f32_16x16x32_bf16 v[12:15], v[182:185], v[206:209], v[12:15]
	v_mfma_f32_16x16x32_bf16 v[8:11], v[174:177], v[214:217], v[8:11]
	v_mfma_f32_16x16x32_bf16 v[4:7], v[182:185], v[214:217], v[4:7]
	s_setprio 0
	s_barrier
	s_add_i32 s68, 0, 0x18000
	v_add_u32_e32 v36, s68, v155
	s_add_i32 s69, 0, 0x1c000
	ds_read_b128 v[150:153], v36
	ds_read_b128 v[158:161], v36 offset:1024
	ds_read_b128 v[162:165], v36 offset:2048
	ds_read_b128 v[166:169], v36 offset:3072
	v_add_u32_e32 v36, s69, v155
	ds_read_b128 v[170:173], v36
	ds_read_b128 v[174:177], v36 offset:1024
	ds_read_b128 v[178:181], v36 offset:2048
	ds_read_b128 v[182:185], v36 offset:3072
	s_add_u32 s26, s26, 0x4000
	s_addc_u32 s27, s27, 0
	s_mov_b32 m0, s35
	ds_read_b128 v[186:189], v157 offset:32768
	ds_read_b128 v[190:193], v157 offset:33792
	ds_read_b128 v[194:197], v157 offset:34816
	ds_read_b128 v[198:201], v157 offset:35840
	ds_read_b128 v[202:205], v157 offset:36864
	ds_read_b128 v[206:209], v157 offset:37888
	ds_read_b128 v[210:213], v157 offset:38912
	ds_read_b128 v[214:217], v157 offset:39936
	global_load_lds_dwordx4 v142, s[26:27]
	s_mov_b32 m0, s36
	s_nop 0
	global_load_lds_dwordx4 v138, s[26:27]
	s_waitcnt vmcnt(8)
	s_waitcnt lgkmcnt(0)
	v_mfma_f32_16x16x32_bf16 v[132:135], v[150:153], v[186:189], v[132:135]
	v_mfma_f32_16x16x32_bf16 v[128:131], v[162:165], v[186:189], v[128:131]
	v_mfma_f32_16x16x32_bf16 v[124:127], v[150:153], v[194:197], v[124:127]
	v_mfma_f32_16x16x32_bf16 v[116:119], v[162:165], v[194:197], v[116:119]
	s_barrier
	s_setprio 1
	v_mfma_f32_16x16x32_bf16 v[108:111], v[150:153], v[202:205], v[108:111]
	v_mfma_f32_16x16x32_bf16 v[100:103], v[162:165], v[202:205], v[100:103]
	v_mfma_f32_16x16x32_bf16 v[92:95], v[150:153], v[210:213], v[92:95]
	v_mfma_f32_16x16x32_bf16 v[84:87], v[162:165], v[210:213], v[84:87]
	v_mfma_f32_16x16x32_bf16 v[132:135], v[158:161], v[190:193], v[132:135]
	v_mfma_f32_16x16x32_bf16 v[128:131], v[166:169], v[190:193], v[128:131]
	v_mfma_f32_16x16x32_bf16 v[124:127], v[158:161], v[198:201], v[124:127]
	v_mfma_f32_16x16x32_bf16 v[116:119], v[166:169], v[198:201], v[116:119]
	v_mfma_f32_16x16x32_bf16 v[108:111], v[158:161], v[206:209], v[108:111]
	v_mfma_f32_16x16x32_bf16 v[100:103], v[166:169], v[206:209], v[100:103]
	v_mfma_f32_16x16x32_bf16 v[92:95], v[158:161], v[214:217], v[92:95]
	v_mfma_f32_16x16x32_bf16 v[84:87], v[166:169], v[214:217], v[84:87]
	v_mfma_f32_16x16x32_bf16 v[120:123], v[170:173], v[186:189], v[120:123]
	v_mfma_f32_16x16x32_bf16 v[112:115], v[178:181], v[186:189], v[112:115]
	v_mfma_f32_16x16x32_bf16 v[104:107], v[170:173], v[194:197], v[104:107]
	v_mfma_f32_16x16x32_bf16 v[96:99], v[178:181], v[194:197], v[96:99]
	v_mfma_f32_16x16x32_bf16 v[88:91], v[170:173], v[202:205], v[88:91]
	v_mfma_f32_16x16x32_bf16 v[80:83], v[178:181], v[202:205], v[80:83]
	v_mfma_f32_16x16x32_bf16 v[76:79], v[170:173], v[210:213], v[76:79]
	v_mfma_f32_16x16x32_bf16 v[72:75], v[178:181], v[210:213], v[72:75]
	v_mfma_f32_16x16x32_bf16 v[120:123], v[174:177], v[190:193], v[120:123]
	v_mfma_f32_16x16x32_bf16 v[112:115], v[182:185], v[190:193], v[112:115]
	v_mfma_f32_16x16x32_bf16 v[104:107], v[174:177], v[198:201], v[104:107]
	v_mfma_f32_16x16x32_bf16 v[96:99], v[182:185], v[198:201], v[96:99]
	v_mfma_f32_16x16x32_bf16 v[88:91], v[174:177], v[206:209], v[88:91]
	v_mfma_f32_16x16x32_bf16 v[80:83], v[182:185], v[206:209], v[80:83]
	v_mfma_f32_16x16x32_bf16 v[76:79], v[174:177], v[214:217], v[76:79]
	v_mfma_f32_16x16x32_bf16 v[72:75], v[182:185], v[214:217], v[72:75]
	s_setprio 0
	s_barrier
; #define PG8_STAGE(bufoff, gbase, voff) do { _Pragma("unroll") for (int _i = 0; _i < 2; ++_i) \
;         __builtin_amdgcn_global_load_lds((const unsigned*)((const char*)(gbase) + (voff)[_i]), (PG8_LAS unsigned*)(lds + (bufoff) + ldsw + _i * 8192), 16, 0, 0); } while (0)
; #define PG8_LDA(dst, b, h) do { _Pragma("unroll") for (int m = 0; m < 4; ++m) _Pragma("unroll") for (int k = 0; k < 2; ++k) dst[m][k] = *(const PG8_LAS bf16x8*)(lds + PG8_SA(b, h) + aoff + m * 2048 + k * 1024); } while (0)
; #define PG8_MMA(ai, bj, At, Bt) do { __builtin_amdgcn_s_setprio(1); _Pragma("unroll") for (int m = 0; m < 4; ++m) _Pragma("unroll") for (int n = 0; n < 2; ++n) _Pragma("unroll") for (int k = 0; k < 2; ++k) \
;         acc[ai][bj][m][n] = __builtin_amdgcn_mfma_f32_16x16x32_bf16(Bt[n][k], At[m][k], acc[ai][bj][m][n], 0, 0, 0); __builtin_amdgcn_s_setprio(0); } while (0)
; #define PG8_WAIT_V(n) asm volatile("s_waitcnt vmcnt(" #n ")" ::: "memory")
; #define PG8_WAIT_L(n) asm volatile("s_waitcnt lgkmcnt(" #n ")" ::: "memory")
; #define PG8_BAR __builtin_amdgcn_s_barrier()
; #define PG8_SCHED __builtin_amdgcn_sched_barrier(0)
; template <class Epi, class Sched, bool ALIGN_EPI = false, bool SP2 = false, bool ABLK = false, bool BBLK = false>
; __device__ __forceinline__ void gemm_phase(PG8_LAS unsigned char* lds, const Gemm g, const Sched& S, const Epi& E) {
;     ...
;         for (int t = 0; t < nt; t += 2) {
;             const bool last = (t == nt - 2);
;             const char* a1 = cA + (size_t)(t + 1) * kstepA;
;             const char* a2 = last ? nA : cA + (size_t)(t + 2) * kstepA; const char* b2 = last ? nB : cB + (size_t)(t + 2) * kstepB;
;     ...
;             PG8_LDA(At, 1, 1); PG8_STAGE(PG8_SB(1, 0), b3, voffB); PG8_STAGE(PG8_SB(1, 1), b3 + hstepB, voffB); PG8_STAGE(PG8_SA(1, 0), a3, voffA);
;             PG8_WAIT_V(8); PG8_WAIT_L(0); PG8_BAR; PG8_MMA(1, 0, At, B0); PG8_MMA(1, 1, At, B1); PG8_BAR; PG8_SCHED;
;     ...
;         if constexpr (ALIGN_EPI) { if (wr == 0) PG8_BAR; }
	s_add_u32 s26, s24, 0x8000
	s_addc_u32 s27, s25, 0
	s_add_i32 s68, s68, s29
	s_mov_b32 m0, s68
	ds_read_b128 v[186:189], v157 offset:49152
	ds_read_b128 v[190:193], v157 offset:50176
	ds_read_b128 v[194:197], v157 offset:51200
	ds_read_b128 v[198:201], v157 offset:52224
	ds_read_b128 v[202:205], v157 offset:53248
	ds_read_b128 v[206:209], v157 offset:54272
	ds_read_b128 v[210:213], v157 offset:55296
	ds_read_b128 v[214:217], v157 offset:56320
	global_load_lds_dwordx4 v140, s[26:27]
	s_add_i32 m0, s68, 0x2000
	s_add_u32 s24, s24, 0xc000
	s_addc_u32 s25, s25, 0
	global_load_lds_dwordx4 v136, s[26:27]
	s_add_i32 s26, s69, s29
	s_mov_b32 m0, s26
	s_nop 0
	global_load_lds_dwordx4 v140, s[24:25]
	s_add_i32 m0, s26, 0x2000
	s_nop 0
	global_load_lds_dwordx4 v136, s[24:25]
	s_mov_b32 m0, s37
	s_nop 0
	global_load_lds_dwordx4 v142, s[22:23]
	s_mov_b32 m0, s62
	s_nop 0
	global_load_lds_dwordx4 v138, s[22:23]
	s_waitcnt vmcnt(8)
	s_waitcnt lgkmcnt(0)
	v_mfma_f32_16x16x32_bf16 v[68:71], v[150:153], v[186:189], v[68:71]
	v_mfma_f32_16x16x32_bf16 v[64:67], v[162:165], v[186:189], v[64:67]
	v_mfma_f32_16x16x32_bf16 v[60:63], v[150:153], v[194:197], v[60:63]
	v_mfma_f32_16x16x32_bf16 v[52:55], v[162:165], v[194:197], v[52:55]
	s_barrier
	s_setprio 1
	v_mfma_f32_16x16x32_bf16 v[44:47], v[150:153], v[202:205], v[44:47]
	v_mfma_f32_16x16x32_bf16 v[32:35], v[162:165], v[202:205], v[32:35]
	v_mfma_f32_16x16x32_bf16 v[24:27], v[150:153], v[210:213], v[24:27]
	v_mfma_f32_16x16x32_bf16 v[16:19], v[162:165], v[210:213], v[16:19]
	v_mfma_f32_16x16x32_bf16 v[68:71], v[158:161], v[190:193], v[68:71]
	v_mfma_f32_16x16x32_bf16 v[64:67], v[166:169], v[190:193], v[64:67]
	v_mfma_f32_16x16x32_bf16 v[60:63], v[158:161], v[198:201], v[60:63]
	v_mfma_f32_16x16x32_bf16 v[52:55], v[166:169], v[198:201], v[52:55]
	v_mfma_f32_16x16x32_bf16 v[44:47], v[158:161], v[206:209], v[44:47]
	v_mfma_f32_16x16x32_bf16 v[32:35], v[166:169], v[206:209], v[32:35]
	v_mfma_f32_16x16x32_bf16 v[24:27], v[158:161], v[214:217], v[24:27]
	v_mfma_f32_16x16x32_bf16 v[16:19], v[166:169], v[214:217], v[16:19]
	v_mfma_f32_16x16x32_bf16 v[56:59], v[170:173], v[186:189], v[56:59]
	v_mfma_f32_16x16x32_bf16 v[48:51], v[178:181], v[186:189], v[48:51]
	v_mfma_f32_16x16x32_bf16 v[40:43], v[170:173], v[194:197], v[40:43]
	v_mfma_f32_16x16x32_bf16 v[28:31], v[178:181], v[194:197], v[28:31]
	v_mfma_f32_16x16x32_bf16 v[20:23], v[170:173], v[202:205], v[20:23]
	v_mfma_f32_16x16x32_bf16 v[12:15], v[178:181], v[202:205], v[12:15]
	v_mfma_f32_16x16x32_bf16 v[8:11], v[170:173], v[210:213], v[8:11]
	v_mfma_f32_16x16x32_bf16 v[4:7], v[178:181], v[210:213], v[4:7]
	v_mfma_f32_16x16x32_bf16 v[56:59], v[174:177], v[190:193], v[56:59]
	v_mfma_f32_16x16x32_bf16 v[48:51], v[182:185], v[190:193], v[48:51]
	v_mfma_f32_16x16x32_bf16 v[40:43], v[174:177], v[198:201], v[40:43]
	v_mfma_f32_16x16x32_bf16 v[28:31], v[182:185], v[198:201], v[28:31]
	v_mfma_f32_16x16x32_bf16 v[20:23], v[174:177], v[206:209], v[20:23]
	v_mfma_f32_16x16x32_bf16 v[12:15], v[182:185], v[206:209], v[12:15]
	v_mfma_f32_16x16x32_bf16 v[8:11], v[174:177], v[214:217], v[8:11]
	v_mfma_f32_16x16x32_bf16 v[4:7], v[182:185], v[214:217], v[4:7]
	s_setprio 0
	s_barrier
	s_add_i32 s13, s13, 2
	s_add_u32 s20, s20, 0x10000
	s_addc_u32 s21, s21, 0
	s_add_u32 s70, s70, 0x10000
	s_addc_u32 s71, s71, 0
	s_cmp_gt_u32 s13, 29
	s_cbranch_scc0 .LBB0_916
	s_and_b64 vcc, exec, s[6:7]
	s_cbranch_vccz .LBB0_919
	s_barrier

; #define LAS __attribute__((address_space(3)))
; __device__ __forceinline__ float bflo(unsigned w) { return __uint_as_float(w << 16); }
; __device__ __forceinline__ float bfhi(unsigned w) { return __uint_as_float(w & 0xffff0000u); }
; __device__ __forceinline__ unsigned pk2(float lo, float hi) { const hwf2 v = {lo, hi}; return __builtin_bit_cast(unsigned, __builtin_convertvector(v, hwbf2)); }
; __device__ __forceinline__ void gla_out_unit(const KP& p, int j, int b, int n, int h, LAS unsigned char* lds, TilesGLA& pre, bool has_next, int b2, int n2, int h2, u32x2 (&sf)[2][8], const bool first) {
;     ...
;       if (first) { const u32x2* SS = (const u32x2*)GP(const bf16_t, WS_SS) + (size_t)ug * 8192 + lane;
; #pragma unroll
;         for (int j2 = 0; j2 < 2; ++j2)
; #pragma unroll
;             for (int dt = 0; dt < 8; ++dt) sf[j2][dt] = SS[(dt * 16 + 2 * wave + j2) * 64]; }
;       LAS u32x4* dv = (LAS u32x4*)(Vs + t_ * 264 + sg * 32); dv[0] = v0; dv[1] = v1; dv[2] = v2; dv[3] = v3;
;       const unsigned qw[8] = {q0.x, q0.y, q0.z, q0.w, q1.x, q1.y, q1.z, q1.w}, kw[8] = {k0.x, k0.y, k0.z, k0.w, k1.x, k1.y, k1.z, k1.w};
;       const float bc[16] = {c0[0], c0[1], c0[2], c0[3], c1[0], c1[1], c1[2], c1[3], c2[0], c2[1], c2[2], c2[3], c3[0], c3[1], c3[2], c3[3]};
;       unsigned qo[8], ko[8];
; #pragma unroll
;       for (int e = 0; e < 8; ++e) { const float e0 = __expf(bc[2 * e]), e1 = __expf(bc[2 * e + 1]);
;           qo[e] = pk2(bflo(qw[e]) * 0.08838834764831845f * e0, bfhi(qw[e]) * 0.08838834764831845f * e1); ko[e] = pk2(bflo(kw[e]) * __builtin_amdgcn_rcpf(e0), bfhi(kw[e]) * __builtin_amdgcn_rcpf(e1)); }
.LBB0_1899:
	v_mov_b32_e32 v120, v0
	s_xor_b64 s[16:17], s[18:19], -1
	s_and_b64 vcc, exec, s[16:17]
	v_readfirstlane_b32 s62, v120
	v_and_b32_e32 v239, 63, v120
	s_ashr_i32 s37, s62, 6
	s_waitcnt vmcnt(0)
	s_cbranch_vccnz .LBB0_1901
	s_lshl_b32 s0, s37, 7
	v_lshlrev_b32_e32 v4, 3, v239
	v_mov_b32_e32 v5, v2
	s_add_i32 s12, s0, 0x400
	v_lshl_add_u64 v[34:35], s[8:9], 0, v[4:5]
	s_ashr_i32 s13, s12, 31
	v_lshl_add_u64 v[6:7], s[12:13], 3, v[34:35]
	s_add_i32 s12, s0, 0x800
	s_ashr_i32 s13, s12, 31
	v_lshl_add_u64 v[8:9], s[12:13], 3, v[34:35]
	s_add_i32 s12, s0, 0xc00
	s_ashr_i32 s13, s12, 31
	v_lshl_add_u64 v[10:11], s[12:13], 3, v[34:35]
	s_add_i32 s12, s0, 0x1000
	s_ashr_i32 s13, s12, 31
	v_lshl_add_u64 v[12:13], s[12:13], 3, v[34:35]
	s_add_i32 s12, s0, 0x1400
	s_ashr_i32 s13, s12, 31
	v_lshl_add_u64 v[14:15], s[12:13], 3, v[34:35]
	s_add_i32 s12, s0, 0x1800
	s_ashr_i32 s13, s12, 31
	v_lshl_add_u64 v[16:17], s[12:13], 3, v[34:35]
	s_add_i32 s12, s0, 0x1c00
	s_ashr_i32 s13, s12, 31
	v_lshl_add_u64 v[18:19], s[12:13], 3, v[34:35]
	s_add_i32 s12, s0, 0x440
	s_ashr_i32 s13, s12, 31
	v_lshl_add_u64 v[22:23], s[12:13], 3, v[34:35]
	s_add_i32 s12, s0, 0x840
	s_ashr_i32 s13, s12, 31
	v_lshl_add_u64 v[24:25], s[12:13], 3, v[34:35]
	s_add_i32 s12, s0, 0xc40
	s_ashr_i32 s13, s12, 31
	v_lshl_add_u64 v[26:27], s[12:13], 3, v[34:35]
	s_add_i32 s12, s0, 0x1040
	s_ashr_i32 s13, s12, 31
	v_lshl_add_u64 v[28:29], s[12:13], 3, v[34:35]
	s_add_i32 s12, s0, 0x1440
	s_ashr_i32 s1, s0, 31
	s_ashr_i32 s13, s12, 31
	v_lshl_add_u64 v[20:21], s[0:1], 3, v[34:35]
	v_lshl_add_u64 v[30:31], s[12:13], 3, v[34:35]
	s_add_i32 s12, s0, 0x1840
	s_addk_i32 s0, 0x1c40
	s_ashr_i32 s13, s12, 31
	s_ashr_i32 s1, s0, 31
	v_lshl_add_u64 v[32:33], s[12:13], 3, v[34:35]
	v_lshl_add_u64 v[34:35], s[0:1], 3, v[34:35]
	global_load_dwordx2 v[4:5], v[20:21], off
	s_nop 0
	global_load_dwordx2 v[14:15], v[14:15], off
	s_nop 0
	global_load_dwordx2 v[16:17], v[16:17], off
	s_nop 0
	global_load_dwordx2 v[6:7], v[6:7], off
	s_nop 0
	global_load_dwordx2 v[8:9], v[8:9], off
	s_nop 0
	global_load_dwordx2 v[10:11], v[10:11], off
	s_nop 0
	global_load_dwordx2 v[12:13], v[12:13], off
	s_nop 0
	global_load_dwordx2 v[18:19], v[18:19], off
	s_nop 0
	global_load_dwordx2 v[20:21], v[20:21], off offset:512
	s_nop 0
	global_load_dwordx2 v[22:23], v[22:23], off
	s_nop 0
	global_load_dwordx2 v[24:25], v[24:25], off
	s_nop 0
	global_load_dwordx2 v[26:27], v[26:27], off
	s_nop 0
	global_load_dwordx2 v[28:29], v[28:29], off
	s_nop 0
	global_load_dwordx2 v[30:31], v[30:31], off
	s_nop 0
	global_load_dwordx2 v[32:33], v[32:33], off
	s_nop 0
	global_load_dwordx2 v[34:35], v[34:35], off
.LBB0_1901:
	v_ashrrev_i32_e32 v3, 3, v120
	v_mul_lo_u32 v36, v3, s79
	v_and_b32_e32 v88, 7, v120
	v_add_u32_e32 v89, 0, v36
	v_lshl_add_u32 v36, v88, 6, v89
	ds_write_b128 v36, v[52:55] offset:34816
	ds_write_b128 v36, v[60:63] offset:34832
	ds_write_b128 v36, v[56:59] offset:34848
	ds_write_b128 v36, v[80:83] offset:34864
	v_mul_f32_e32 v36, 0x3fb8aa3b, v84
	v_mul_f32_e32 v37, 0x3fb8aa3b, v85
	v_exp_f32_e32 v36, v36
	v_exp_f32_e32 v37, v37
	v_lshlrev_b32_e32 v38, 16, v64
	v_and_b32_e32 v39, 0xffff0000, v64
	v_pk_mul_f32 v[38:39], v[38:39], s[94:95] op_sel_hi:[1,0]
	v_lshlrev_b32_e32 v238, 5, v88
	v_pk_mul_f32 v[38:39], v[38:39], v[36:37]
	v_rcp_f32_e32 v36, v36
	v_rcp_f32_e32 v37, v37
	v_cvt_pk_bf16_f32 v90, v38, v39
	v_lshlrev_b32_e32 v38, 16, v48
	v_and_b32_e32 v39, 0xffff0000, v48
	v_pk_mul_f32 v[36:37], v[36:37], v[38:39]
	v_lshlrev_b32_e32 v38, 16, v65
	v_cvt_pk_bf16_f32 v94, v36, v37
	v_mul_f32_e32 v36, 0x3fb8aa3b, v86
	v_mul_f32_e32 v37, 0x3fb8aa3b, v87
	v_exp_f32_e32 v36, v36
	v_exp_f32_e32 v37, v37
	v_and_b32_e32 v39, 0xffff0000, v65
	v_pk_mul_f32 v[38:39], v[38:39], s[94:95] op_sel_hi:[1,0]
	v_cmp_gt_i32_e64 s[0:1], s80, v120
	v_pk_mul_f32 v[38:39], v[38:39], v[36:37]
	v_rcp_f32_e32 v36, v36
	v_rcp_f32_e32 v37, v37
	v_cvt_pk_bf16_f32 v91, v38, v39
	v_lshlrev_b32_e32 v38, 16, v49
	v_and_b32_e32 v39, 0xffff0000, v49
	v_pk_mul_f32 v[36:37], v[36:37], v[38:39]
	v_lshlrev_b32_e32 v38, 16, v66
	v_cvt_pk_bf16_f32 v95, v36, v37
	v_mul_f32_e32 v36, 0x3fb8aa3b, v76
	v_mul_f32_e32 v37, 0x3fb8aa3b, v77
	v_exp_f32_e32 v36, v36
	v_exp_f32_e32 v37, v37
	v_and_b32_e32 v39, 0xffff0000, v66
	v_pk_mul_f32 v[38:39], v[38:39], s[94:95] op_sel_hi:[1,0]
	s_nop 0
	v_pk_mul_f32 v[38:39], v[38:39], v[36:37]
	v_rcp_f32_e32 v36, v36
	v_rcp_f32_e32 v37, v37
	v_cvt_pk_bf16_f32 v92, v38, v39
	v_lshlrev_b32_e32 v38, 16, v50
	v_and_b32_e32 v39, 0xffff0000, v50
	v_pk_mul_f32 v[36:37], v[36:37], v[38:39]
	v_lshlrev_b32_e32 v38, 16, v67
	v_cvt_pk_bf16_f32 v96, v36, v37
	v_mul_f32_e32 v36, 0x3fb8aa3b, v78
	v_mul_f32_e32 v37, 0x3fb8aa3b, v79
	v_exp_f32_e32 v36, v36
	v_exp_f32_e32 v37, v37
	v_and_b32_e32 v39, 0xffff0000, v67
	v_pk_mul_f32 v[38:39], v[38:39], s[94:95] op_sel_hi:[1,0]
	s_nop 0
	v_pk_mul_f32 v[38:39], v[38:39], v[36:37]
	v_rcp_f32_e32 v36, v36
	v_rcp_f32_e32 v37, v37
	v_cvt_pk_bf16_f32 v93, v38, v39
	v_lshlrev_b32_e32 v38, 16, v51
	v_and_b32_e32 v39, 0xffff0000, v51
	v_pk_mul_f32 v[36:37], v[36:37], v[38:39]
	v_lshlrev_b32_e32 v38, 16, v40
; #define LAS __attribute__((address_space(3)))
; __device__ __forceinline__ float bflo(unsigned w) { return __uint_as_float(w << 16); }
; __device__ __forceinline__ float bfhi(unsigned w) { return __uint_as_float(w & 0xffff0000u); }
; __device__ __forceinline__ unsigned pk2(float lo, float hi) { const hwf2 v = {lo, hi}; return __builtin_bit_cast(unsigned, __builtin_convertvector(v, hwbf2)); }
; __device__ __forceinline__ void gla_out_load(const KP& p, TilesGLA& T, int b, int n, int h, int tid) {
;     const int t_ = tid >> 3, sg = tid & 7, row0 = b * SEQ + n * 64, ug = (b * NCH + n) * 4 + h; const bf16_t* zr = GP(const bf16_t, WS_HB) + (size_t)(row0 + t_) * EV_NP;
;     const u32x4* sq = (const u32x4*)(zr + 2048 + h * 128 + sg * 16); const u32x4* sk = (const u32x4*)(zr + 2560 + h * 128 + sg * 16); const u32x4* sv = (const u32x4*)(zr + 3072 + h * 256 + sg * 32);
;     const f32x4* sb = (const f32x4*)(GP(const float, WS_BC) + (size_t)ug * 8192 + t_ * 128 + sg * 16);
;     T.q[0] = sq[0]; T.q[1] = sq[1]; T.k[0] = sk[0]; T.k[1] = sk[1];
; #pragma unroll
;     for (int c = 0; c < 4; ++c) { T.v[c] = sv[c]; T.c[c] = sb[c]; }
;     if (tid < 128) T.dec = GP(const float, WS_DEC)[(size_t)ug * 128 + tid];
; }
; __device__ __forceinline__ void gla_out_unit(const KP& p, int j, int b, int n, int h, LAS unsigned char* lds, TilesGLA& pre, bool has_next, int b2, int n2, int h2, u32x2 (&sf)[2][8], const bool first) {
;     ...
;       for (int e = 0; e < 8; ++e) { const float e0 = __expf(bc[2 * e]), e1 = __expf(bc[2 * e + 1]);
;           qo[e] = pk2(bflo(qw[e]) * 0.08838834764831845f * e0, bfhi(qw[e]) * 0.08838834764831845f * e1); ko[e] = pk2(bflo(kw[e]) * __builtin_amdgcn_rcpf(e0), bfhi(kw[e]) * __builtin_amdgcn_rcpf(e1)); }
;       LAS u32x4* dq = (LAS u32x4*)(Qd + t_ * 136 + sg * 16); dq[0] = (u32x4){qo[0], qo[1], qo[2], qo[3]}; dq[1] = (u32x4){qo[4], qo[5], qo[6], qo[7]};
;       LAS u32x4* dk = (LAS u32x4*)(Ki + t_ * 136 + sg * 16); dk[0] = (u32x4){ko[0], ko[1], ko[2], ko[3]}; dk[1] = (u32x4){ko[4], ko[5], ko[6], ko[7]}; }
;     if (tid < 128) DEs[tid] = pre.dec;
;     if (has_next) gla_out_load(p, pre, b2, n2, h2, tid);
	v_cvt_pk_bf16_f32 v97, v36, v37
	v_mul_f32_e32 v36, 0x3fb8aa3b, v72
	v_mul_f32_e32 v37, 0x3fb8aa3b, v73
	v_exp_f32_e32 v36, v36
	v_exp_f32_e32 v37, v37
	v_and_b32_e32 v39, 0xffff0000, v40
	v_pk_mul_f32 v[38:39], v[38:39], s[94:95] op_sel_hi:[1,0]
	s_nop 0
	v_pk_mul_f32 v[38:39], v[38:39], v[36:37]
	v_rcp_f32_e32 v36, v36
	v_rcp_f32_e32 v37, v37
	v_cvt_pk_bf16_f32 v98, v38, v39
	v_lshlrev_b32_e32 v38, 16, v44
	v_and_b32_e32 v39, 0xffff0000, v44
	v_pk_mul_f32 v[36:37], v[36:37], v[38:39]
	v_lshlrev_b32_e32 v38, 16, v41
	v_cvt_pk_bf16_f32 v102, v36, v37
	v_mul_f32_e32 v36, 0x3fb8aa3b, v74
	v_mul_f32_e32 v37, 0x3fb8aa3b, v75
	v_exp_f32_e32 v36, v36
	v_exp_f32_e32 v37, v37
	v_and_b32_e32 v39, 0xffff0000, v41
	v_pk_mul_f32 v[38:39], v[38:39], s[94:95] op_sel_hi:[1,0]
	s_nop 0
	v_pk_mul_f32 v[38:39], v[38:39], v[36:37]
	v_rcp_f32_e32 v36, v36
	v_rcp_f32_e32 v37, v37
	v_cvt_pk_bf16_f32 v99, v38, v39
	v_lshlrev_b32_e32 v38, 16, v45
	v_and_b32_e32 v39, 0xffff0000, v45
	v_pk_mul_f32 v[36:37], v[36:37], v[38:39]
	v_lshlrev_b32_e32 v38, 16, v42
	v_cvt_pk_bf16_f32 v103, v36, v37
	v_mul_f32_e32 v36, 0x3fb8aa3b, v68
	v_mul_f32_e32 v37, 0x3fb8aa3b, v69
	v_exp_f32_e32 v36, v36
	v_exp_f32_e32 v37, v37
	v_and_b32_e32 v39, 0xffff0000, v42
	v_pk_mul_f32 v[38:39], v[38:39], s[94:95] op_sel_hi:[1,0]
	s_nop 0
	v_pk_mul_f32 v[38:39], v[38:39], v[36:37]
	v_rcp_f32_e32 v36, v36
	v_rcp_f32_e32 v37, v37
	v_cvt_pk_bf16_f32 v100, v38, v39
	v_lshlrev_b32_e32 v38, 16, v46
	v_and_b32_e32 v39, 0xffff0000, v46
	v_pk_mul_f32 v[36:37], v[36:37], v[38:39]
	v_lshlrev_b32_e32 v38, 16, v43
	v_cvt_pk_bf16_f32 v104, v36, v37
	v_mul_f32_e32 v36, 0x3fb8aa3b, v70
	v_mul_f32_e32 v37, 0x3fb8aa3b, v71
	v_exp_f32_e32 v36, v36
	v_exp_f32_e32 v37, v37
	v_and_b32_e32 v39, 0xffff0000, v43
	v_pk_mul_f32 v[38:39], v[38:39], s[94:95] op_sel_hi:[1,0]
	s_nop 0
	v_pk_mul_f32 v[38:39], v[38:39], v[36:37]
	v_rcp_f32_e32 v36, v36
	v_rcp_f32_e32 v37, v37
	v_cvt_pk_bf16_f32 v101, v38, v39
	v_lshlrev_b32_e32 v38, 16, v47
	v_and_b32_e32 v39, 0xffff0000, v47
	v_pk_mul_f32 v[36:37], v[36:37], v[38:39]
	s_nop 0
	v_cvt_pk_bf16_f32 v105, v36, v37
	v_lshlrev_b32_e32 v36, 8, v3
	v_sub_u32_e32 v36, v89, v36
	v_add_u32_e32 v36, v36, v238
	ds_write_b128 v36, v[90:93]
	ds_write_b128 v36, v[98:101] offset:16
	ds_write_b128 v36, v[94:97] offset:17408
	ds_write_b128 v36, v[102:105] offset:17424
	s_and_saveexec_b64 s[20:21], s[0:1]
	v_lshl_add_u32 v36, v120, 2, 0
	v_add_u32_e32 v36, 0x13800, v36
	ds_write_b32 v36, v237
	s_or_b64 exec, exec, s[20:21]
	s_or_b64 s[12:13], s[18:19], s[6:7]
	s_andn2_b64 vcc, exec, s[12:13]
	v_lshlrev_b32_e32 v230, 1, v238
	s_cbranch_vccnz .LBB0_1907
	s_and_b64 s[12:13], s[18:19], exec
	s_cselect_b32 s12, s25, s28
	s_cselect_b32 s13, s29, s30
	s_cselect_b32 s21, s27, s31
	s_lshl_b32 s20, s12, 13
	s_lshl_b32 s22, s13, 6
	s_or_b32 s22, s22, s20
	s_lshl_b32 s12, s12, 9
	s_lshl_b32 s13, s13, 2
	s_or_b32 s12, s13, s12
	v_add_u32_e32 v38, s22, v3
	v_mov_b64_e32 v[36:37], s[96:97]
	v_lshlrev_b32_e32 v46, 4, v88
	s_or_b32 s20, s12, s21
	v_mad_i64_i32 v[36:37], s[12:13], v38, s39, v[36:37]
	s_lshl_b32 s82, s21, 8
	v_lshlrev_b32_e32 v38, 1, v46
	v_mov_b32_e32 v39, v2
	v_lshl_add_u64 v[40:41], v[36:37], 0, s[82:83]
	v_lshl_add_u64 v[38:39], v[40:41], 0, v[38:39]
	s_mov_b64 s[12:13], 0x1000
	s_lshl_b32 s82, s21, 9
	v_lshl_add_u64 v[40:41], v[38:39], 0, s[12:13]
	s_mov_b64 s[12:13], 0x1400
	v_lshl_add_u64 v[36:37], v[36:37], 0, s[82:83]
	v_mov_b32_e32 v231, v2
	v_lshl_add_u64 v[44:45], v[38:39], 0, s[12:13]
	v_lshl_add_u64 v[36:37], v[36:37], 0, v[230:231]
	s_mov_b64 s[12:13], 0x1800
	s_ashr_i32 s21, s20, 31
	v_lshl_add_u64 v[80:81], v[36:37], 0, s[12:13]
	s_lshl_b64 s[12:13], s[20:21], 15
	s_add_u32 s12, s95, s12
	v_lshlrev_b32_e32 v42, 7, v3
	s_addc_u32 s13, s76, s13
	v_ashrrev_i32_e32 v43, 31, v42
	v_add_co_u32_e32 v38, vcc, s57, v38
	v_lshl_add_u64 v[42:43], v[42:43], 2, s[12:13]
	v_lshlrev_b32_e32 v46, 2, v46
	v_mov_b32_e32 v47, v2
	v_addc_co_u32_e32 v39, vcc, 0, v39, vcc
	v_lshl_add_u64 v[84:85], v[42:43], 0, v[46:47]
	v_add_co_u32_e32 v36, vcc, 0x1000, v36
	global_load_dwordx4 v[40:43], v[40:41], off offset:16
	s_nop 0
	global_load_dwordx4 v[44:47], v[44:45], off offset:16
	v_addc_co_u32_e32 v37, vcc, 0, v37, vcc
	global_load_dwordx4 v[48:51], v[38:39], off offset:1024
	global_load_dwordx4 v[52:55], v[36:37], off offset:2048
	global_load_dwordx4 v[56:59], v[80:81], off offset:32
	global_load_dwordx4 v[60:63], v[80:81], off offset:16
	global_load_dwordx4 v[64:67], v[38:39], off
	global_load_dwordx4 v[68:71], v[84:85], off offset:48
	global_load_dwordx4 v[72:75], v[84:85], off offset:32
	global_load_dwordx4 v[76:79], v[84:85], off offset:16
	s_nop 0
	global_load_dwordx4 v[80:83], v[80:81], off offset:48
	s_nop 0
	global_load_dwordx4 v[84:87], v[84:85], off
	s_and_saveexec_b64 s[22:23], s[0:1]
	s_cbranch_execz .LBB0_1906
	s_lshl_b64 s[0:1], s[20:21], 9
	v_readlane_b32 s12, v252, 51
	s_add_u32 s0, s12, s0
	v_readlane_b32 s12, v252, 52
	s_addc_u32 s1, s12, s1
	v_ashrrev_i32_e32 v121, 31, v120
	v_lshl_add_u64 v[36:37], v[120:121], 2, s[0:1]
	global_load_dword v237, v[36:37], off

; #define MFMA16(a, b, c) __builtin_amdgcn_mfma_f32_16x16x32_bf16((a), (b), (c), 0, 0, 0)
; __device__ __forceinline__ void gla_out_unit(const KP& p, int j, int b, int n, int h, LAS unsigned char* lds, TilesGLA& pre, bool has_next, int b2, int n2, int h2, u32x2 (&sf)[2][8], const bool first) {
;     ...
;       for (int s2 = 0; s2 < 2; ++s2)
; #pragma unroll
;           for (int i = 0; i < 4; ++i) { const int t = tt * 16 + g4 * 4 + i, s = (stb + s2) * 16 + (lane & 15); Ps[t * 72 + s] = (s <= t) ? f2bf(acc[s2][i]) : (bf16_t)0; } }
;     __syncthreads();
;     f32x4 o[2][4];
; #pragma unroll
;     for (int j2 = 0; j2 < 2; ++j2)
; #pragma unroll
;         for (int tt = 0; tt < 4; ++tt) o[j2][tt] = F4ZERO;
; #pragma unroll
;     for (int k2 = 0; k2 < 2; ++k2) { bf16x8 bfr[4];
; #pragma unroll
;         for (int tt = 0; tt < 4; ++tt) bfr[tt] = lds_frag(Ps, 72, 16 * tt, 32 * k2, lane);
; #pragma unroll
;         for (int j2 = 0; j2 < 2; ++j2) { const bf16x8 a = tr_frag(Vs, 264, 32 * k2 + 8 * g4, 32 * k2 + 8 * g4 + 4, 16 * (2 * wave + j2), lane);
; #pragma unroll
;             for (int tt = 0; tt < 4; ++tt) o[j2][tt] = MFMA16(a, bfr[tt], o[j2][tt]); } }
; #pragma unroll
;     for (int ks = 0; ks < 4; ++ks) { bf16x8 bfr[4];
; #pragma unroll
;         for (int tt = 0; tt < 4; ++tt) bfr[tt] = lds_frag_perm(Qd, 136, 16 * tt, 32 * ks, lane);
; #pragma unroll
;         for (int j2 = 0; j2 < 2; ++j2) { const u32x4 w = {sf[j2][2 * ks].x, sf[j2][2 * ks].y, sf[j2][2 * ks + 1].x, sf[j2][2 * ks + 1].y}; const bf16x8 a = __builtin_bit_cast(bf16x8, w);
; #pragma unroll
;             for (int tt = 0; tt < 4; ++tt) o[j2][tt] = MFMA16(a, bfr[tt], o[j2][tt]); } }
.LBB0_1911:
	v_lshrrev_b32_e32 v36, 4, v239
	v_lshl_or_b32 v37, v36, 2, s12
	v_lshl_add_u32 v38, v98, 1, s14
	v_cvt_pk_bf16_f32 v39, v92, s0
	v_cmp_le_i32_e32 vcc, v98, v37
	v_mul_lo_u32 v92, v37, s59
	v_add_u32_e32 v99, v38, v92
	v_cndmask_b32_e32 v39, 0, v39, vcc
	ds_write_b16 v99, v39
	v_or_b32_e32 v39, 1, v37
	v_cvt_pk_bf16_f32 v93, v93, s0
	v_cmp_le_i32_e32 vcc, v98, v39
	v_add_u32_e32 v99, 0x90, v92
	v_add_u32_e32 v100, v38, v99
	v_cndmask_b32_e32 v93, 0, v93, vcc
	ds_write_b16 v100, v93
	v_or_b32_e32 v93, 2, v37
	v_cvt_pk_bf16_f32 v94, v94, s0
	v_cmp_le_i32_e32 vcc, v98, v93
	v_add_u32_e32 v100, 0x120, v92
	v_add_u32_e32 v101, v38, v100
	v_cndmask_b32_e32 v94, 0, v94, vcc
	ds_write_b16 v101, v94
	v_or_b32_e32 v94, 3, v37
	v_cvt_pk_bf16_f32 v95, v95, s0
	v_cmp_le_i32_e32 vcc, v98, v94
	v_add_u32_e32 v101, 0x1b0, v92
	v_add_u32_e32 v38, v38, v101
	v_cndmask_b32_e32 v95, 0, v95, vcc
	ds_write_b16 v38, v95
	v_or_b32_e32 v38, 16, v98
	v_cvt_pk_bf16_f32 v88, v88, s0
	v_cmp_le_i32_e32 vcc, v38, v37
	v_and_b32_e32 v241, 48, v120
	s_nop 0
	v_cndmask_b32_e32 v37, 0, v88, vcc
	v_lshlrev_b32_e32 v88, 1, v38
	v_add3_u32 v92, s14, v92, v88
	ds_write_b16 v92, v37
	v_cvt_pk_bf16_f32 v37, v89, s0
	v_cmp_le_i32_e32 vcc, v38, v39
	v_add3_u32 v39, s14, v99, v88
	s_nop 0
	v_cndmask_b32_e32 v37, 0, v37, vcc
	ds_write_b16 v39, v37
	v_cvt_pk_bf16_f32 v37, v90, s0
	v_cmp_le_i32_e32 vcc, v38, v93
	v_add3_u32 v39, s14, v100, v88
	s_nop 0
	v_cndmask_b32_e32 v37, 0, v37, vcc
	ds_write_b16 v39, v37
	v_cvt_pk_bf16_f32 v37, v91, s0
	v_cmp_le_i32_e32 vcc, v38, v94
	v_add3_u32 v38, s14, v101, v88
	v_lshlrev_b32_e32 v39, 2, v239
	v_cndmask_b32_e32 v37, 0, v37, vcc
	ds_write_b16 v38, v37
	v_bfe_u32 v38, v120, 2, 2
	v_and_b32_e32 v121, 12, v39
	v_lshl_or_b32 v122, v36, 3, v38
	v_lshlrev_b32_e32 v37, 1, v97
	v_lshl_add_u32 v39, v121, 1, 0
	v_mul_u32_u24_e32 v88, 0x90, v240
	v_mul_u32_u24_e32 v123, 0x210, v122
	s_lshl_b32 s0, s37, 6
	v_add3_u32 v37, s14, v37, v88
	v_add3_u32 v36, v39, v123, s0
	s_waitcnt lgkmcnt(0)
	s_barrier
	s_waitcnt vmcnt(12)
	ds_read_b128 v[88:91], v37
	ds_read_b128 v[92:95], v37 offset:2304
	ds_read_b128 v[98:101], v37 offset:4608
	ds_read_b128 v[102:105], v37 offset:6912
	ds_read_b64_tr_b16 v[108:109], v36 offset:36928
	ds_read_b64_tr_b16 v[106:107], v36 offset:34816
	ds_read_b64_tr_b16 v[110:111], v36 offset:34848
	ds_read_b64_tr_b16 v[112:113], v36 offset:36960
	s_waitcnt lgkmcnt(2)
	v_mfma_f32_16x16x32_bf16 v[114:117], v[106:109], v[88:91], 0
	s_andn2_b64 vcc, exec, s[18:19]
	v_mfma_f32_16x16x32_bf16 v[124:127], v[106:109], v[92:95], 0
	v_mfma_f32_16x16x32_bf16 v[128:131], v[106:109], v[98:101], 0
	v_mfma_f32_16x16x32_bf16 v[106:109], v[106:109], v[102:105], 0
	s_waitcnt lgkmcnt(0)
	v_mfma_f32_16x16x32_bf16 v[88:91], v[110:113], v[88:91], 0
	v_mfma_f32_16x16x32_bf16 v[92:95], v[110:113], v[92:95], 0
	v_mfma_f32_16x16x32_bf16 v[98:101], v[110:113], v[98:101], 0
	v_mfma_f32_16x16x32_bf16 v[102:105], v[110:113], v[102:105], 0
	ds_read_b128 v[110:113], v37 offset:64
	ds_read_b128 v[132:135], v37 offset:2368
	ds_read_b128 v[136:139], v37 offset:4672
	ds_read_b128 v[140:143], v37 offset:6976
	ds_read_b64_tr_b16 v[144:145], v36 offset:51712
	ds_read_b64_tr_b16 v[146:147], v36 offset:53824
	s_waitcnt lgkmcnt(0)
	v_mfma_f32_16x16x32_bf16 v[114:117], v[144:147], v[110:113], v[114:117]
	v_mfma_f32_16x16x32_bf16 v[124:127], v[144:147], v[132:135], v[124:127]
	v_mfma_f32_16x16x32_bf16 v[128:131], v[144:147], v[136:139], v[128:131]
	v_mfma_f32_16x16x32_bf16 v[106:109], v[144:147], v[140:143], v[106:109]
	ds_read_b64_tr_b16 v[144:145], v36 offset:51744
	ds_read_b64_tr_b16 v[146:147], v36 offset:53856
	v_mul_u32_u24_e32 v36, 0x110, v240
	v_add3_u32 v36, 0, v96, v36
	v_add_u32_e32 v37, 0x1000, v36
	v_add_u32_e32 v38, 0x2000, v36
	v_add_u32_e32 v39, 0x3000, v36
	s_waitcnt lgkmcnt(0)
	v_mfma_f32_16x16x32_bf16 v[88:91], v[144:147], v[110:113], v[88:91]
	ds_read2_b64 v[110:113], v36 offset1:4
	v_mfma_f32_16x16x32_bf16 v[92:95], v[144:147], v[132:135], v[92:95]
	ds_read2_b64 v[132:135], v37 offset0:32 offset1:36
	v_mfma_f32_16x16x32_bf16 v[98:101], v[144:147], v[136:139], v[98:101]
	ds_read2_b64 v[136:139], v38 offset0:64 offset1:68
	v_mfma_f32_16x16x32_bf16 v[102:105], v[144:147], v[140:143], v[102:105]
	ds_read2_b64 v[140:143], v39 offset0:96 offset1:100
	s_waitcnt lgkmcnt(3)
	v_mfma_f32_16x16x32_bf16 v[114:117], v[4:7], v[110:113], v[114:117]
	s_waitcnt lgkmcnt(2)
	v_mfma_f32_16x16x32_bf16 v[124:127], v[4:7], v[132:135], v[124:127]
	s_waitcnt lgkmcnt(1)
	v_mfma_f32_16x16x32_bf16 v[128:131], v[4:7], v[136:139], v[128:131]
	s_waitcnt lgkmcnt(0)
	v_mfma_f32_16x16x32_bf16 v[106:109], v[4:7], v[140:143], v[106:109]
	v_mfma_f32_16x16x32_bf16 v[88:91], v[20:23], v[110:113], v[88:91]
	v_mfma_f32_16x16x32_bf16 v[92:95], v[20:23], v[132:135], v[92:95]
	v_mfma_f32_16x16x32_bf16 v[96:99], v[20:23], v[136:139], v[98:101]
	v_mfma_f32_16x16x32_bf16 v[100:103], v[20:23], v[140:143], v[102:105]
	ds_read2_b64 v[110:113], v36 offset0:8 offset1:12
	ds_read2_b64 v[132:135], v37 offset0:40 offset1:44
	ds_read2_b64 v[136:139], v38 offset0:72 offset1:76
	ds_read2_b64 v[140:143], v39 offset0:104 offset1:108
	s_waitcnt lgkmcnt(3)
	v_mfma_f32_16x16x32_bf16 v[114:117], v[8:11], v[110:113], v[114:117]
	s_waitcnt lgkmcnt(2)
	v_mfma_f32_16x16x32_bf16 v[124:127], v[8:11], v[132:135], v[124:127]
	s_waitcnt lgkmcnt(1)
	v_mfma_f32_16x16x32_bf16 v[128:131], v[8:11], v[136:139], v[128:131]
	s_waitcnt lgkmcnt(0)
; #define LAS __attribute__((address_space(3)))
; __device__ __forceinline__ float bflo(unsigned w) { return __uint_as_float(w << 16); }
; __device__ __forceinline__ float bfhi(unsigned w) { return __uint_as_float(w & 0xffff0000u); }
; __device__ __forceinline__ unsigned pk2(float lo, float hi) { const hwf2 v = {lo, hi}; return __builtin_bit_cast(unsigned, __builtin_convertvector(v, hwbf2)); }
; #define MFMA16(a, b, c) __builtin_amdgcn_mfma_f32_16x16x32_bf16((a), (b), (c), 0, 0, 0)
; __device__ __forceinline__ void gla_out_unit(const KP& p, int j, int b, int n, int h, LAS unsigned char* lds, TilesGLA& pre, bool has_next, int b2, int n2, int h2, u32x2 (&sf)[2][8], const bool first) {
;     ...
;     for (int ks = 0; ks < 4; ++ks) { bf16x8 bfr[4];
; #pragma unroll
;         for (int tt = 0; tt < 4; ++tt) bfr[tt] = lds_frag_perm(Qd, 136, 16 * tt, 32 * ks, lane);
; #pragma unroll
;         for (int j2 = 0; j2 < 2; ++j2) { const u32x4 w = {sf[j2][2 * ks].x, sf[j2][2 * ks].y, sf[j2][2 * ks + 1].x, sf[j2][2 * ks + 1].y}; const bf16x8 a = __builtin_bit_cast(bf16x8, w);
; #pragma unroll
;             for (int tt = 0; tt < 4; ++tt) o[j2][tt] = MFMA16(a, bfr[tt], o[j2][tt]); } }
;     if (first) {
;         const LAS float* decp = DEs + 4 * g4;
; #pragma unroll
;         for (int j2 = 0; j2 < 2; ++j2) { const bf16x8 bv0 = tr_frag(Vs, 264, 8 * g4, 8 * g4 + 4, 16 * (2 * wave + j2), lane), bv1 = tr_frag(Vs, 264, 32 + 8 * g4, 36 + 8 * g4, 16 * (2 * wave + j2), lane);
; #pragma unroll
;             for (int dq = 0; dq < 8; dq += 2) { f32x4 sa[2];
; #pragma unroll
;                 for (int d2 = 0; d2 < 2; ++d2) { const int dt = dq + d2; sa[d2] = (f32x4){bflo(sf[j2][dt].x), bfhi(sf[j2][dt].x), bflo(sf[j2][dt].y), bfhi(sf[j2][dt].y)};
;                     sa[d2] = MFMA16(tr_frag(Ki, 136, 8 * g4, 8 * g4 + 4, 16 * dt, lane), bv0, sa[d2]); sa[d2] = MFMA16(tr_frag(Ki, 136, 32 + 8 * g4, 36 + 8 * g4, 16 * dt, lane), bv1, sa[d2]); }
; #pragma unroll
;                 for (int d2 = 0; d2 < 2; ++d2) { const int dt = dq + d2; const f32x4 dc = *(const LAS f32x4*)(decp + 16 * dt); const f32x4 r = sa[d2] * dc; sf[j2][dt].x = pk2(r[0], r[1]); sf[j2][dt].y = pk2(r[2], r[3]); } } } }
	v_mfma_f32_16x16x32_bf16 v[104:107], v[8:11], v[140:143], v[106:109]
	v_mfma_f32_16x16x32_bf16 v[88:91], v[24:27], v[110:113], v[88:91]
	v_mfma_f32_16x16x32_bf16 v[92:95], v[24:27], v[132:135], v[92:95]
	v_mfma_f32_16x16x32_bf16 v[96:99], v[24:27], v[136:139], v[96:99]
	v_mfma_f32_16x16x32_bf16 v[100:103], v[24:27], v[140:143], v[100:103]
	ds_read2_b64 v[108:111], v36 offset0:16 offset1:20
	ds_read2_b64 v[132:135], v37 offset0:48 offset1:52
	ds_read2_b64 v[136:139], v38 offset0:80 offset1:84
	ds_read2_b64 v[140:143], v39 offset0:112 offset1:116
	s_waitcnt lgkmcnt(3)
	v_mfma_f32_16x16x32_bf16 v[112:115], v[12:15], v[108:111], v[114:117]
	s_waitcnt lgkmcnt(2)
	v_mfma_f32_16x16x32_bf16 v[116:119], v[12:15], v[132:135], v[124:127]
	s_waitcnt lgkmcnt(1)
	v_mfma_f32_16x16x32_bf16 v[124:127], v[12:15], v[136:139], v[128:131]
	s_waitcnt lgkmcnt(0)
	v_mfma_f32_16x16x32_bf16 v[128:131], v[12:15], v[140:143], v[104:107]
	v_mfma_f32_16x16x32_bf16 v[88:91], v[28:31], v[108:111], v[88:91]
	v_mfma_f32_16x16x32_bf16 v[108:111], v[28:31], v[132:135], v[92:95]
	v_mfma_f32_16x16x32_bf16 v[132:135], v[28:31], v[136:139], v[96:99]
	v_mfma_f32_16x16x32_bf16 v[136:139], v[28:31], v[140:143], v[100:103]
	s_nop 2
	ds_read2_b64 v[100:103], v36 offset0:24 offset1:28
	ds_read2_b64 v[140:143], v37 offset0:56 offset1:60
	ds_read2_b64 v[144:147], v38 offset0:88 offset1:92
	ds_read2_b64 v[148:151], v39 offset0:120 offset1:124
	s_waitcnt lgkmcnt(3)
	v_mfma_f32_16x16x32_bf16 v[112:115], v[16:19], v[100:103], v[112:115]
	s_waitcnt lgkmcnt(2)
	v_mfma_f32_16x16x32_bf16 v[104:107], v[16:19], v[140:143], v[116:119]
	s_waitcnt lgkmcnt(1)
	v_mfma_f32_16x16x32_bf16 v[96:99], v[16:19], v[144:147], v[124:127]
	s_waitcnt lgkmcnt(0)
	v_mfma_f32_16x16x32_bf16 v[92:95], v[16:19], v[148:151], v[128:131]
	v_mfma_f32_16x16x32_bf16 v[116:119], v[32:35], v[100:103], v[88:91]
	v_mfma_f32_16x16x32_bf16 v[108:111], v[32:35], v[140:143], v[108:111]
	v_mfma_f32_16x16x32_bf16 v[100:103], v[32:35], v[144:147], v[132:135]
	v_mfma_f32_16x16x32_bf16 v[88:91], v[32:35], v[148:151], v[136:139]
	s_cbranch_vccnz .LBB0_1913
	v_add_u32_e32 v36, 0, v241
	v_or_b32_e32 v38, 4, v122
	s_lshl_b32 s0, s37, 5
	v_add_u32_e32 v220, 0x13800, v36
	v_lshlrev_b32_e32 v36, 1, v121
	v_mul_u32_u24_e32 v39, 0x210, v38
	v_add3_u32 v37, 0, v123, v36
	v_add3_u32 v36, 0, v39, v36
	v_lshlrev_b32_e32 v121, 8, v122
	v_lshlrev_b32_e32 v38, 8, v38
	s_lshl_b32 s0, s0, 1
	v_add_u32_e32 v39, 0x39c0, v36
	v_add_u32_e32 v120, 0x4200, v36
	v_sub_u32_e32 v216, v37, v121
	v_sub_u32_e32 v218, v36, v38
	v_or_b32_e32 v38, 0x2000, v121
	v_add_u32_e32 v37, s0, v37
	v_sub_u32_e32 v222, v39, v38
	v_or_b32_e32 v38, 0x2400, v121
	v_add_u32_e32 v36, s0, v36
	ds_read_b64_tr_b16 v[172:173], v37 offset:34816
	ds_read_b64_tr_b16 v[124:125], v37 offset:34848
	ds_read_b64_tr_b16 v[174:175], v36 offset:34816
	ds_read_b64_tr_b16 v[126:127], v36 offset:34848
	v_add_u32_e32 v37, s0, v120
	v_sub_u32_e32 v221, v120, v38
	v_add_u32_e32 v36, s0, v39
	ds_read_b64_tr_b16 v[170:171], v37 offset:34816
	ds_read_b64_tr_b16 v[122:123], v37 offset:34848
	ds_read_b64_tr_b16 v[168:169], v36 offset:34816
	ds_read_b64_tr_b16 v[120:121], v36 offset:34848
	ds_read_b64_tr_b16 v[144:145], v216 offset:17408
	ds_read_b64_tr_b16 v[128:129], v216 offset:17440
	ds_read_b64_tr_b16 v[146:147], v218 offset:17408
	ds_read_b64_tr_b16 v[130:131], v218 offset:17440
	v_lshlrev_b32_e32 v132, 16, v4
	v_and_b32_e32 v133, 0xffff0000, v4
	v_lshlrev_b32_e32 v134, 16, v5
	v_and_b32_e32 v135, 0xffff0000, v5
	v_lshlrev_b32_e32 v4, 16, v6
	v_and_b32_e32 v5, 0xffff0000, v6
	s_waitcnt lgkmcnt(1)
	v_mfma_f32_16x16x32_bf16 v[136:139], v[144:147], v[172:175], v[132:135]
	ds_read_b64_tr_b16 v[150:151], v221 offset:17408
	s_nop 1
	ds_read_b64_tr_b16 v[134:135], v221 offset:17440
	ds_read_b64_tr_b16 v[148:149], v222 offset:17408
	ds_read_b64_tr_b16 v[132:133], v222 offset:17440
	v_lshlrev_b32_e32 v6, 16, v7
	v_and_b32_e32 v7, 0xffff0000, v7
	s_waitcnt lgkmcnt(1)
	v_mfma_f32_16x16x32_bf16 v[140:143], v[148:151], v[168:171], v[136:139]
	s_nop 2
	ds_read_b128 v[136:139], v220
	v_mfma_f32_16x16x32_bf16 v[4:7], v[128:131], v[172:175], v[4:7]
	s_waitcnt lgkmcnt(1)
	v_mfma_f32_16x16x32_bf16 v[152:155], v[132:135], v[168:171], v[4:7]
	s_waitcnt lgkmcnt(0)
	s_nop 4
	v_pk_mul_f32 v[6:7], v[142:143], v[138:139]
	v_pk_mul_f32 v[4:5], v[140:141], v[136:137]
	ds_read_b128 v[140:143], v220 offset:64
	ds_read_b64_tr_b16 v[156:157], v216 offset:17472
	ds_read_b64_tr_b16 v[158:159], v218 offset:17472
	v_cvt_pk_bf16_f32 v4, v4, v5
	v_cvt_pk_bf16_f32 v5, v6, v7
	s_waitcnt lgkmcnt(2)
	v_pk_mul_f32 v[36:37], v[154:155], v[142:143]
	v_pk_mul_f32 v[6:7], v[152:153], v[140:141]
	v_lshlrev_b32_e32 v152, 16, v8
	v_and_b32_e32 v153, 0xffff0000, v8
	v_lshlrev_b32_e32 v154, 16, v9
	v_and_b32_e32 v155, 0xffff0000, v9
	v_lshlrev_b32_e32 v8, 16, v10
	v_and_b32_e32 v9, 0xffff0000, v10
	s_waitcnt lgkmcnt(0)
	v_mfma_f32_16x16x32_bf16 v[160:163], v[156:159], v[172:175], v[152:155]
	s_nop 2
	ds_read_b64_tr_b16 v[152:153], v222 offset:17472
	ds_read_b64_tr_b16 v[154:155], v221 offset:17472
	v_lshlrev_b32_e32 v10, 16, v11
	v_and_b32_e32 v11, 0xffff0000, v11
	s_waitcnt lgkmcnt(0)
	v_mfma_f32_16x16x32_bf16 v[180:183], v[152:155], v[168:171], v[160:163]
	s_nop 2
	ds_read_b64_tr_b16 v[160:161], v216 offset:17504
	ds_read_b64_tr_b16 v[162:163], v218 offset:17504
	ds_read_b64_tr_b16 v[164:165], v222 offset:17504
	ds_read_b64_tr_b16 v[166:167], v221 offset:17504
	ds_read_b128 v[176:179], v220 offset:128
	s_waitcnt lgkmcnt(3)
	v_mfma_f32_16x16x32_bf16 v[8:11], v[160:163], v[172:175], v[8:11]
	v_cvt_pk_bf16_f32 v6, v6, v7
	v_cvt_pk_bf16_f32 v7, v36, v37
	s_waitcnt lgkmcnt(1)
; #define LAS __attribute__((address_space(3)))
; __device__ __forceinline__ float bflo(unsigned w) { return __uint_as_float(w << 16); }
; __device__ __forceinline__ float bfhi(unsigned w) { return __uint_as_float(w & 0xffff0000u); }
; __device__ __forceinline__ unsigned pk2(float lo, float hi) { const hwf2 v = {lo, hi}; return __builtin_bit_cast(unsigned, __builtin_convertvector(v, hwbf2)); }
; #define MFMA16(a, b, c) __builtin_amdgcn_mfma_f32_16x16x32_bf16((a), (b), (c), 0, 0, 0)
; __device__ __forceinline__ void gla_out_unit(const KP& p, int j, int b, int n, int h, LAS unsigned char* lds, TilesGLA& pre, bool has_next, int b2, int n2, int h2, u32x2 (&sf)[2][8], const bool first) {
;     ...
;         for (int j2 = 0; j2 < 2; ++j2) { const bf16x8 bv0 = tr_frag(Vs, 264, 8 * g4, 8 * g4 + 4, 16 * (2 * wave + j2), lane), bv1 = tr_frag(Vs, 264, 32 + 8 * g4, 36 + 8 * g4, 16 * (2 * wave + j2), lane);
; #pragma unroll
;             for (int dq = 0; dq < 8; dq += 2) { f32x4 sa[2];
; #pragma unroll
;                 for (int d2 = 0; d2 < 2; ++d2) { const int dt = dq + d2; sa[d2] = (f32x4){bflo(sf[j2][dt].x), bfhi(sf[j2][dt].x), bflo(sf[j2][dt].y), bfhi(sf[j2][dt].y)};
;                     sa[d2] = MFMA16(tr_frag(Ki, 136, 8 * g4, 8 * g4 + 4, 16 * dt, lane), bv0, sa[d2]); sa[d2] = MFMA16(tr_frag(Ki, 136, 32 + 8 * g4, 36 + 8 * g4, 16 * dt, lane), bv1, sa[d2]); }
; #pragma unroll
;                 for (int d2 = 0; d2 < 2; ++d2) { const int dt = dq + d2; const f32x4 dc = *(const LAS f32x4*)(decp + 16 * dt); const f32x4 r = sa[d2] * dc; sf[j2][dt].x = pk2(r[0], r[1]); sf[j2][dt].y = pk2(r[2], r[3]); } } } }
	v_mfma_f32_16x16x32_bf16 v[184:187], v[164:167], v[168:171], v[8:11]
	s_waitcnt lgkmcnt(0)
	s_nop 2
	v_pk_mul_f32 v[10:11], v[182:183], v[178:179]
	v_pk_mul_f32 v[8:9], v[180:181], v[176:177]
	ds_read_b128 v[180:183], v220 offset:192
	ds_read_b64_tr_b16 v[188:189], v216 offset:17536
	ds_read_b64_tr_b16 v[190:191], v218 offset:17536
	v_cvt_pk_bf16_f32 v8, v8, v9
	v_cvt_pk_bf16_f32 v9, v10, v11
	s_waitcnt lgkmcnt(2)
	v_pk_mul_f32 v[36:37], v[186:187], v[182:183]
	v_pk_mul_f32 v[10:11], v[184:185], v[180:181]
	v_lshlrev_b32_e32 v184, 16, v12
	v_and_b32_e32 v185, 0xffff0000, v12
	v_lshlrev_b32_e32 v186, 16, v13
	v_and_b32_e32 v187, 0xffff0000, v13
	v_lshlrev_b32_e32 v12, 16, v14
	v_and_b32_e32 v13, 0xffff0000, v14
	s_waitcnt lgkmcnt(0)
	v_mfma_f32_16x16x32_bf16 v[192:195], v[188:191], v[172:175], v[184:187]
	s_nop 2
	ds_read_b64_tr_b16 v[184:185], v222 offset:17536
	ds_read_b64_tr_b16 v[186:187], v221 offset:17536
	ds_read_b64_tr_b16 v[204:205], v216 offset:17568
	ds_read_b64_tr_b16 v[206:207], v218 offset:17568
	v_lshlrev_b32_e32 v14, 16, v15
	s_waitcnt lgkmcnt(2)
	v_mfma_f32_16x16x32_bf16 v[196:199], v[184:187], v[168:171], v[192:195]
	v_and_b32_e32 v15, 0xffff0000, v15
	ds_read_b64_tr_b16 v[200:201], v222 offset:17568
	ds_read_b64_tr_b16 v[202:203], v221 offset:17568
	ds_read_b128 v[192:195], v220 offset:256
	s_waitcnt lgkmcnt(3)
	v_mfma_f32_16x16x32_bf16 v[12:15], v[204:207], v[172:175], v[12:15]
	v_cvt_pk_bf16_f32 v10, v10, v11
	v_cvt_pk_bf16_f32 v11, v36, v37
	s_waitcnt lgkmcnt(1)
	v_mfma_f32_16x16x32_bf16 v[208:211], v[200:203], v[168:171], v[12:15]
	s_waitcnt lgkmcnt(0)
	s_nop 2
	v_pk_mul_f32 v[14:15], v[198:199], v[194:195]
	v_pk_mul_f32 v[12:13], v[196:197], v[192:193]
	ds_read_b128 v[196:199], v220 offset:320
	ds_read_b64_tr_b16 v[212:213], v216 offset:17600
	ds_read_b64_tr_b16 v[214:215], v218 offset:17600
	v_cvt_pk_bf16_f32 v12, v12, v13
	v_cvt_pk_bf16_f32 v13, v14, v15
	s_waitcnt lgkmcnt(2)
	v_pk_mul_f32 v[36:37], v[210:211], v[198:199]
	v_pk_mul_f32 v[14:15], v[208:209], v[196:197]
	v_lshlrev_b32_e32 v208, 16, v16
	v_and_b32_e32 v209, 0xffff0000, v16
	v_lshlrev_b32_e32 v210, 16, v17
	v_and_b32_e32 v211, 0xffff0000, v17
	v_lshlrev_b32_e32 v16, 16, v18
	v_and_b32_e32 v17, 0xffff0000, v18
	s_waitcnt lgkmcnt(0)
	v_mfma_f32_16x16x32_bf16 v[242:245], v[212:215], v[172:175], v[208:211]
	s_nop 2
	ds_read_b64_tr_b16 v[208:209], v222 offset:17600
	ds_read_b64_tr_b16 v[210:211], v221 offset:17600
	ds_read_b64_tr_b16 v[216:217], v216 offset:17632
	ds_read_b64_tr_b16 v[218:219], v218 offset:17632
	v_lshlrev_b32_e32 v18, 16, v19
	v_and_b32_e32 v19, 0xffff0000, v19
	s_waitcnt lgkmcnt(2)
	v_mfma_f32_16x16x32_bf16 v[242:245], v[208:211], v[168:171], v[242:245]
	v_cvt_pk_bf16_f32 v14, v14, v15
	v_cvt_pk_bf16_f32 v15, v36, v37
	s_waitcnt lgkmcnt(0)
	v_mfma_f32_16x16x32_bf16 v[16:19], v[216:219], v[172:175], v[16:19]
	ds_read_b64_tr_b16 v[172:173], v222 offset:17632
	ds_read_b64_tr_b16 v[174:175], v221 offset:17632
	s_waitcnt lgkmcnt(0)
	v_mfma_f32_16x16x32_bf16 v[246:249], v[172:175], v[168:171], v[16:19]
	ds_read_b128 v[168:171], v220 offset:384
	ds_read_b128 v[220:223], v220 offset:448
	s_waitcnt lgkmcnt(1)
	s_nop 0
	v_pk_mul_f32 v[18:19], v[244:245], v[170:171]
	v_pk_mul_f32 v[16:17], v[242:243], v[168:169]
	v_lshlrev_b32_e32 v242, 16, v20
	v_and_b32_e32 v243, 0xffff0000, v20
	v_lshlrev_b32_e32 v244, 16, v21
	v_and_b32_e32 v245, 0xffff0000, v21
	v_lshlrev_b32_e32 v20, 16, v22
	v_and_b32_e32 v21, 0xffff0000, v22
	v_mfma_f32_16x16x32_bf16 v[144:147], v[144:147], v[124:127], v[242:245]
	v_lshlrev_b32_e32 v22, 16, v23
	v_and_b32_e32 v23, 0xffff0000, v23
	v_cvt_pk_bf16_f32 v16, v16, v17
	v_mfma_f32_16x16x32_bf16 v[144:147], v[148:151], v[120:123], v[144:147]
	v_cvt_pk_bf16_f32 v17, v18, v19
	s_waitcnt lgkmcnt(0)
; #define LAS __attribute__((address_space(3)))
; __device__ __forceinline__ float bflo(unsigned w) { return __uint_as_float(w << 16); }
; __device__ __forceinline__ float bfhi(unsigned w) { return __uint_as_float(w & 0xffff0000u); }
; __device__ __forceinline__ unsigned pk2(float lo, float hi) { const hwf2 v = {lo, hi}; return __builtin_bit_cast(unsigned, __builtin_convertvector(v, hwbf2)); }
; #define MFMA16(a, b, c) __builtin_amdgcn_mfma_f32_16x16x32_bf16((a), (b), (c), 0, 0, 0)
; __device__ __forceinline__ void gla_out_unit(const KP& p, int j, int b, int n, int h, LAS unsigned char* lds, TilesGLA& pre, bool has_next, int b2, int n2, int h2, u32x2 (&sf)[2][8], const bool first) {
;     ...
;         for (int j2 = 0; j2 < 2; ++j2) { const bf16x8 bv0 = tr_frag(Vs, 264, 8 * g4, 8 * g4 + 4, 16 * (2 * wave + j2), lane), bv1 = tr_frag(Vs, 264, 32 + 8 * g4, 36 + 8 * g4, 16 * (2 * wave + j2), lane);
; #pragma unroll
;             for (int dq = 0; dq < 8; dq += 2) { f32x4 sa[2];
; #pragma unroll
;                 for (int d2 = 0; d2 < 2; ++d2) { const int dt = dq + d2; sa[d2] = (f32x4){bflo(sf[j2][dt].x), bfhi(sf[j2][dt].x), bflo(sf[j2][dt].y), bfhi(sf[j2][dt].y)};
;                     sa[d2] = MFMA16(tr_frag(Ki, 136, 8 * g4, 8 * g4 + 4, 16 * dt, lane), bv0, sa[d2]); sa[d2] = MFMA16(tr_frag(Ki, 136, 32 + 8 * g4, 36 + 8 * g4, 16 * dt, lane), bv1, sa[d2]); }
; #pragma unroll
;                 for (int d2 = 0; d2 < 2; ++d2) { const int dt = dq + d2; const f32x4 dc = *(const LAS f32x4*)(decp + 16 * dt); const f32x4 r = sa[d2] * dc; sf[j2][dt].x = pk2(r[0], r[1]); sf[j2][dt].y = pk2(r[2], r[3]); } } } }
	v_pk_mul_f32 v[36:37], v[248:249], v[222:223]
	v_pk_mul_f32 v[18:19], v[246:247], v[220:221]
	v_mfma_f32_16x16x32_bf16 v[20:23], v[128:131], v[124:127], v[20:23]
	v_cvt_pk_bf16_f32 v18, v18, v19
	v_cvt_pk_bf16_f32 v19, v36, v37
	v_mfma_f32_16x16x32_bf16 v[128:131], v[132:135], v[120:123], v[20:23]
	s_nop 4
	v_mul_f32_e64 v22, v138, v146
	v_mul_f32_e64 v23, v139, v147
	v_pk_mul_f32 v[20:21], v[136:137], v[144:145]
	v_pk_mul_f32 v[36:37], v[142:143], v[130:131]
	v_cvt_pk_bf16_f32 v20, v20, v21
	v_cvt_pk_bf16_f32 v21, v22, v23
	v_pk_mul_f32 v[22:23], v[140:141], v[128:129]
	v_lshlrev_b32_e32 v128, 16, v24
	v_and_b32_e32 v129, 0xffff0000, v24
	v_lshlrev_b32_e32 v130, 16, v25
	v_and_b32_e32 v131, 0xffff0000, v25
	v_lshlrev_b32_e32 v24, 16, v26
	v_and_b32_e32 v25, 0xffff0000, v26
	v_mfma_f32_16x16x32_bf16 v[128:131], v[156:159], v[124:127], v[128:131]
	v_lshlrev_b32_e32 v26, 16, v27
	v_and_b32_e32 v27, 0xffff0000, v27
	v_cvt_pk_bf16_f32 v22, v22, v23
	v_mfma_f32_16x16x32_bf16 v[128:131], v[152:155], v[120:123], v[128:131]
	v_cvt_pk_bf16_f32 v23, v36, v37
	v_mfma_f32_16x16x32_bf16 v[24:27], v[160:163], v[124:127], v[24:27]
	v_mfma_f32_16x16x32_bf16 v[132:135], v[164:167], v[120:123], v[24:27]
	s_nop 6
	v_mul_f32_e64 v26, v178, v130
	v_mul_f32_e64 v27, v179, v131
	v_pk_mul_f32 v[24:25], v[176:177], v[128:129]
	v_lshlrev_b32_e32 v128, 16, v28
	v_and_b32_e32 v129, 0xffff0000, v28
	v_lshlrev_b32_e32 v130, 16, v29
	v_and_b32_e32 v131, 0xffff0000, v29
	v_lshlrev_b32_e32 v28, 16, v30
	v_and_b32_e32 v29, 0xffff0000, v30
	v_mfma_f32_16x16x32_bf16 v[128:131], v[188:191], v[124:127], v[128:131]
	v_lshlrev_b32_e32 v30, 16, v31
	v_and_b32_e32 v31, 0xffff0000, v31
	v_cvt_pk_bf16_f32 v24, v24, v25
	v_mfma_f32_16x16x32_bf16 v[128:131], v[184:187], v[120:123], v[128:131]
	v_cvt_pk_bf16_f32 v25, v26, v27
	v_pk_mul_f32 v[36:37], v[182:183], v[134:135]
	v_pk_mul_f32 v[26:27], v[180:181], v[132:133]
	v_mfma_f32_16x16x32_bf16 v[28:31], v[204:207], v[124:127], v[28:31]
	v_cvt_pk_bf16_f32 v26, v26, v27
	v_cvt_pk_bf16_f32 v27, v36, v37
	v_mfma_f32_16x16x32_bf16 v[132:135], v[200:203], v[120:123], v[28:31]
	s_nop 4
	v_mul_f32_e64 v30, v194, v130
	v_mul_f32_e64 v31, v195, v131
	v_pk_mul_f32 v[28:29], v[192:193], v[128:129]
	v_lshlrev_b32_e32 v128, 16, v32
	v_and_b32_e32 v129, 0xffff0000, v32
	v_lshlrev_b32_e32 v130, 16, v33
	v_and_b32_e32 v131, 0xffff0000, v33
	v_lshlrev_b32_e32 v32, 16, v34
	v_and_b32_e32 v33, 0xffff0000, v34
	v_mfma_f32_16x16x32_bf16 v[128:131], v[212:215], v[124:127], v[128:131]
	v_lshlrev_b32_e32 v34, 16, v35
	v_and_b32_e32 v35, 0xffff0000, v35
	v_cvt_pk_bf16_f32 v28, v28, v29
	v_mfma_f32_16x16x32_bf16 v[128:131], v[208:211], v[120:123], v[128:131]
	v_cvt_pk_bf16_f32 v29, v30, v31
	v_pk_mul_f32 v[36:37], v[198:199], v[134:135]
	v_pk_mul_f32 v[30:31], v[196:197], v[132:133]
	v_mfma_f32_16x16x32_bf16 v[32:35], v[216:219], v[124:127], v[32:35]
	v_cvt_pk_bf16_f32 v30, v30, v31
	v_cvt_pk_bf16_f32 v31, v36, v37
	v_mfma_f32_16x16x32_bf16 v[120:123], v[172:175], v[120:123], v[32:35]
	s_nop 4
	v_mul_f32_e64 v34, v170, v130
	v_mul_f32_e64 v35, v171, v131
	v_pk_mul_f32 v[32:33], v[168:169], v[128:129]
	v_pk_mul_f32 v[36:37], v[222:223], v[122:123]
	v_cvt_pk_bf16_f32 v32, v32, v33
	v_cvt_pk_bf16_f32 v33, v34, v35
	v_pk_mul_f32 v[34:35], v[220:221], v[120:121]
	v_mov_b64_e32 v[218:219], v[224:225]
	v_mov_b64_e32 v[220:221], v[226:227]
	v_cvt_pk_bf16_f32 v34, v34, v35
	v_cvt_pk_bf16_f32 v35, v36, v37

; #define PG8_STAGE(bufoff, gbase, voff) do { _Pragma("unroll") for (int _i = 0; _i < 2; ++_i) \
;         __builtin_amdgcn_global_load_lds((const unsigned*)((const char*)(gbase) + (voff)[_i]), (PG8_LAS unsigned*)(lds + (bufoff) + ldsw + _i * 8192), 16, 0, 0); } while (0)
; #define PG8_LDA(dst, b, h) do { _Pragma("unroll") for (int m = 0; m < 4; ++m) _Pragma("unroll") for (int k = 0; k < 2; ++k) dst[m][k] = *(const PG8_LAS bf16x8*)(lds + PG8_SA(b, h) + aoff + m * 2048 + k * 1024); } while (0)
; #define PG8_WAIT_V(n) asm volatile("s_waitcnt vmcnt(" #n ")" ::: "memory")
; #define PG8_WAIT_L(n) asm volatile("s_waitcnt lgkmcnt(" #n ")" ::: "memory")
; template <class Epi, class Sched, bool ALIGN_EPI = false, bool SP2 = false, bool ABLK = false, bool BBLK = false>
; __device__ __forceinline__ void gemm_phase(PG8_LAS unsigned char* lds, const Gemm g, const Sched& S, const Epi& E) {
;     ...
;         for (int t = 0; t < nt; t += 2) {
;             const bool last = (t == nt - 2);
;             const char* a1 = cA + (size_t)(t + 1) * kstepA;
;             const char* a2 = last ? nA : cA + (size_t)(t + 2) * kstepA; const char* b2 = last ? nB : cB + (size_t)(t + 2) * kstepB;
;             const char* a3 = a2 + kstepA; const char* b3 = b2 + kstepB;
;             if (last && has_next) S.a_ready(nxt);
;             if constexpr (SP2) {
;             PG8_LDB(B0, 0, 0); PG8_LDB(B1, 0, 1); PG8_SCHED; PG8_LDA(At, 0, 0); PG8_STAGE(PG8_SA(1, 1), a1 + hstepA, voffA);
;             PG8_WAIT_V(8); PG8_WAIT_L(0); PG8_BAR; PG8_MMA(0, 0, At, B0); PG8_MMA(0, 1, At, B1); PG8_BAR; PG8_SCHED;
;             PG8_LDA(At, 0, 1); PG8_STAGE(PG8_SB(0, 0), b2, voffB); PG8_STAGE(PG8_SB(0, 1), b2 + hstepB, voffB); PG8_STAGE(PG8_SA(0, 0), a2, voffA);
;             PG8_WAIT_V(8); PG8_WAIT_L(0); PG8_BAR; PG8_MMA(1, 0, At, B0); PG8_MMA(1, 1, At, B1); PG8_BAR; PG8_SCHED;
;             PG8_LDB(B0, 1, 0); PG8_LDB(B1, 1, 1); PG8_SCHED; PG8_LDA(At, 1, 0); PG8_STAGE(PG8_SA(0, 1), a2 + hstepA, voffA);
;             PG8_WAIT_V(8); PG8_WAIT_L(0); PG8_BAR; PG8_MMA(0, 0, At, B0); PG8_MMA(0, 1, At, B1); PG8_BAR; PG8_SCHED;
;             PG8_LDA(At, 1, 1); PG8_STAGE(PG8_SB(1, 0), b3, voffB); PG8_STAGE(PG8_SB(1, 1), b3 + hstepB, voffB); PG8_STAGE(PG8_SA(1, 0), a3, voffA);
;             PG8_WAIT_V(8); PG8_WAIT_L(0); PG8_BAR; PG8_MMA(1, 0, At, B0); PG8_MMA(1, 1, At, B1); PG8_BAR; PG8_SCHED;
.LBB0_2111:
	s_add_u32 s24, s22, 0x4000
	s_addc_u32 s25, s23, 0
	s_cmp_eq_u32 s13, 28
	s_cselect_b32 s28, s17, s24
	s_cselect_b32 s29, s12, s25
	s_cselect_b32 s26, s77, s82
	s_cselect_b32 s27, s11, vcc_lo
	s_add_u32 s24, s28, 0x8000
	s_addc_u32 s25, s29, 0
	s_add_i32 s68, 0, 0x10000
	v_add_u32_e32 v151, s68, v148
	s_add_i32 s88, 0, 0x14000
	ds_read_b128 v[36:39], v151
	ds_read_b128 v[152:155], v151 offset:1024
	ds_read_b128 v[156:159], v151 offset:2048
	ds_read_b128 v[160:163], v151 offset:3072
	v_add_u32_e32 v151, s88, v148
	ds_read_b128 v[164:167], v151
	ds_read_b128 v[168:171], v151 offset:1024
	ds_read_b128 v[172:175], v151 offset:2048
	ds_read_b128 v[176:179], v151 offset:3072
	s_add_i32 m0, s9, 0xc000
	ds_read_b128 v[180:183], v150
	ds_read_b128 v[184:187], v150 offset:1024
	ds_read_b128 v[188:191], v150 offset:2048
	ds_read_b128 v[192:195], v150 offset:3072
	ds_read_b128 v[196:199], v150 offset:4096
	ds_read_b128 v[200:203], v150 offset:5120
	ds_read_b128 v[204:207], v150 offset:6144
	ds_read_b128 v[208:211], v150 offset:7168
	global_load_lds_dwordx4 v144, s[22:23]
	s_add_i32 m0, s9, 0xe000
	s_nop 0
	global_load_lds_dwordx4 v146, s[22:23]
	s_waitcnt vmcnt(8)
	s_waitcnt lgkmcnt(0)
	v_mfma_f32_16x16x32_bf16 v[132:135], v[36:39], v[180:183], v[132:135]
	v_mfma_f32_16x16x32_bf16 v[128:131], v[156:159], v[180:183], v[128:131]
	v_mfma_f32_16x16x32_bf16 v[124:127], v[36:39], v[188:191], v[124:127]
	v_mfma_f32_16x16x32_bf16 v[120:123], v[156:159], v[188:191], v[120:123]
	s_barrier
	s_setprio 1
	v_mfma_f32_16x16x32_bf16 v[108:111], v[36:39], v[196:199], v[108:111]
	v_mfma_f32_16x16x32_bf16 v[104:107], v[156:159], v[196:199], v[104:107]
	v_mfma_f32_16x16x32_bf16 v[92:95], v[36:39], v[204:207], v[92:95]
	v_mfma_f32_16x16x32_bf16 v[88:91], v[156:159], v[204:207], v[88:91]
	v_mfma_f32_16x16x32_bf16 v[132:135], v[152:155], v[184:187], v[132:135]
	v_mfma_f32_16x16x32_bf16 v[128:131], v[160:163], v[184:187], v[128:131]
	v_mfma_f32_16x16x32_bf16 v[124:127], v[152:155], v[192:195], v[124:127]
	v_mfma_f32_16x16x32_bf16 v[120:123], v[160:163], v[192:195], v[120:123]
	v_mfma_f32_16x16x32_bf16 v[108:111], v[152:155], v[200:203], v[108:111]
	v_mfma_f32_16x16x32_bf16 v[104:107], v[160:163], v[200:203], v[104:107]
	v_mfma_f32_16x16x32_bf16 v[92:95], v[152:155], v[208:211], v[92:95]
	v_mfma_f32_16x16x32_bf16 v[88:91], v[160:163], v[208:211], v[88:91]
	v_mfma_f32_16x16x32_bf16 v[116:119], v[164:167], v[180:183], v[116:119]
	v_mfma_f32_16x16x32_bf16 v[112:115], v[172:175], v[180:183], v[112:115]
	v_mfma_f32_16x16x32_bf16 v[100:103], v[164:167], v[188:191], v[100:103]
	v_mfma_f32_16x16x32_bf16 v[96:99], v[172:175], v[188:191], v[96:99]
	v_mfma_f32_16x16x32_bf16 v[84:87], v[164:167], v[196:199], v[84:87]
	v_mfma_f32_16x16x32_bf16 v[80:83], v[172:175], v[196:199], v[80:83]
	v_mfma_f32_16x16x32_bf16 v[76:79], v[164:167], v[204:207], v[76:79]
	v_mfma_f32_16x16x32_bf16 v[72:75], v[172:175], v[204:207], v[72:75]
	v_mfma_f32_16x16x32_bf16 v[116:119], v[168:171], v[184:187], v[116:119]
	v_mfma_f32_16x16x32_bf16 v[112:115], v[176:179], v[184:187], v[112:115]
	v_mfma_f32_16x16x32_bf16 v[100:103], v[168:171], v[192:195], v[100:103]
	v_mfma_f32_16x16x32_bf16 v[96:99], v[176:179], v[192:195], v[96:99]
	v_mfma_f32_16x16x32_bf16 v[84:87], v[168:171], v[200:203], v[84:87]
	v_mfma_f32_16x16x32_bf16 v[80:83], v[176:179], v[200:203], v[80:83]
	v_mfma_f32_16x16x32_bf16 v[76:79], v[168:171], v[208:211], v[76:79]
	v_mfma_f32_16x16x32_bf16 v[72:75], v[176:179], v[208:211], v[72:75]
	s_setprio 0
	s_barrier
	s_add_i32 s68, s68, s34
	s_mov_b32 m0, s68
	ds_read_b128 v[180:183], v150 offset:16384
	ds_read_b128 v[184:187], v150 offset:17408
	ds_read_b128 v[188:191], v150 offset:18432
	ds_read_b128 v[192:195], v150 offset:19456
	ds_read_b128 v[196:199], v150 offset:20480
	ds_read_b128 v[200:203], v150 offset:21504
	ds_read_b128 v[204:207], v150 offset:22528
	ds_read_b128 v[208:211], v150 offset:23552
	global_load_lds_dwordx4 v138, s[26:27]
	s_add_i32 m0, s68, 0x2000
	s_add_u32 s68, s26, 0x4000
	s_addc_u32 s69, s27, 0
	s_add_i32 s88, s88, s34
	global_load_lds_dwordx4 v142, s[26:27]
	s_mov_b32 m0, s88
	s_nop 0
	global_load_lds_dwordx4 v138, s[68:69]
	s_add_i32 m0, s88, 0x2000
	s_nop 0
	global_load_lds_dwordx4 v142, s[68:69]
	s_mov_b32 m0, s9
	s_nop 0
	global_load_lds_dwordx4 v136, s[28:29]
	s_mov_b32 m0, s35
	s_nop 0
	global_load_lds_dwordx4 v140, s[28:29]
	s_waitcnt vmcnt(8)
	s_waitcnt lgkmcnt(0)
	v_mfma_f32_16x16x32_bf16 v[68:71], v[36:39], v[180:183], v[68:71]
	v_mfma_f32_16x16x32_bf16 v[64:67], v[156:159], v[180:183], v[64:67]
	v_mfma_f32_16x16x32_bf16 v[60:63], v[36:39], v[188:191], v[60:63]
	v_mfma_f32_16x16x32_bf16 v[56:59], v[156:159], v[188:191], v[56:59]
	s_barrier
; #define PG8_STAGE(bufoff, gbase, voff) do { _Pragma("unroll") for (int _i = 0; _i < 2; ++_i) \
;         __builtin_amdgcn_global_load_lds((const unsigned*)((const char*)(gbase) + (voff)[_i]), (PG8_LAS unsigned*)(lds + (bufoff) + ldsw + _i * 8192), 16, 0, 0); } while (0)
; #define PG8_LDA(dst, b, h) do { _Pragma("unroll") for (int m = 0; m < 4; ++m) _Pragma("unroll") for (int k = 0; k < 2; ++k) dst[m][k] = *(const PG8_LAS bf16x8*)(lds + PG8_SA(b, h) + aoff + m * 2048 + k * 1024); } while (0)
; #define PG8_LDB(dst, b, h) do { _Pragma("unroll") for (int n = 0; n < 2; ++n) _Pragma("unroll") for (int k = 0; k < 2; ++k) dst[n][k] = *(const PG8_LAS bf16x8*)(lds + PG8_SB(b, h) + boff + n * 2048 + k * 1024); } while (0)
; #define PG8_MMA(ai, bj, At, Bt) do { __builtin_amdgcn_s_setprio(1); _Pragma("unroll") for (int m = 0; m < 4; ++m) _Pragma("unroll") for (int n = 0; n < 2; ++n) _Pragma("unroll") for (int k = 0; k < 2; ++k) \
;         acc[ai][bj][m][n] = __builtin_amdgcn_mfma_f32_16x16x32_bf16(Bt[n][k], At[m][k], acc[ai][bj][m][n], 0, 0, 0); __builtin_amdgcn_s_setprio(0); } while (0)
; template <class Epi, class Sched, bool ALIGN_EPI = false, bool SP2 = false, bool ABLK = false, bool BBLK = false>
; __device__ __forceinline__ void gemm_phase(PG8_LAS unsigned char* lds, const Gemm g, const Sched& S, const Epi& E) {
;     ...
;             PG8_LDB(B0, 0, 0); PG8_LDB(B1, 0, 1); PG8_SCHED; PG8_LDA(At, 0, 0); PG8_STAGE(PG8_SA(1, 1), a1 + hstepA, voffA);
;             PG8_WAIT_V(8); PG8_WAIT_L(0); PG8_BAR; PG8_MMA(0, 0, At, B0); PG8_MMA(0, 1, At, B1); PG8_BAR; PG8_SCHED;
;             PG8_LDA(At, 0, 1); PG8_STAGE(PG8_SB(0, 0), b2, voffB); PG8_STAGE(PG8_SB(0, 1), b2 + hstepB, voffB); PG8_STAGE(PG8_SA(0, 0), a2, voffA);
;             PG8_WAIT_V(8); PG8_WAIT_L(0); PG8_BAR; PG8_MMA(1, 0, At, B0); PG8_MMA(1, 1, At, B1); PG8_BAR; PG8_SCHED;
;             PG8_LDB(B0, 1, 0); PG8_LDB(B1, 1, 1); PG8_SCHED; PG8_LDA(At, 1, 0); PG8_STAGE(PG8_SA(0, 1), a2 + hstepA, voffA);
;             PG8_WAIT_V(8); PG8_WAIT_L(0); PG8_BAR; PG8_MMA(0, 0, At, B0); PG8_MMA(0, 1, At, B1); PG8_BAR; PG8_SCHED;
;             PG8_LDA(At, 1, 1); PG8_STAGE(PG8_SB(1, 0), b3, voffB); PG8_STAGE(PG8_SB(1, 1), b3 + hstepB, voffB); PG8_STAGE(PG8_SA(1, 0), a3, voffA);
;             PG8_WAIT_V(8); PG8_WAIT_L(0); PG8_BAR; PG8_MMA(1, 0, At, B0); PG8_MMA(1, 1, At, B1); PG8_BAR; PG8_SCHED;
	s_setprio 1
	v_mfma_f32_16x16x32_bf16 v[44:47], v[36:39], v[196:199], v[44:47]
	v_mfma_f32_16x16x32_bf16 v[40:43], v[156:159], v[196:199], v[40:43]
	v_mfma_f32_16x16x32_bf16 v[24:27], v[36:39], v[204:207], v[24:27]
	v_mfma_f32_16x16x32_bf16 v[20:23], v[156:159], v[204:207], v[20:23]
	v_mfma_f32_16x16x32_bf16 v[68:71], v[152:155], v[184:187], v[68:71]
	v_mfma_f32_16x16x32_bf16 v[64:67], v[160:163], v[184:187], v[64:67]
	v_mfma_f32_16x16x32_bf16 v[60:63], v[152:155], v[192:195], v[60:63]
	v_mfma_f32_16x16x32_bf16 v[56:59], v[160:163], v[192:195], v[56:59]
	v_mfma_f32_16x16x32_bf16 v[44:47], v[152:155], v[200:203], v[44:47]
	v_mfma_f32_16x16x32_bf16 v[40:43], v[160:163], v[200:203], v[40:43]
	v_mfma_f32_16x16x32_bf16 v[24:27], v[152:155], v[208:211], v[24:27]
	v_mfma_f32_16x16x32_bf16 v[20:23], v[160:163], v[208:211], v[20:23]
	v_mfma_f32_16x16x32_bf16 v[48:51], v[172:175], v[180:183], v[48:51]
	v_mfma_f32_16x16x32_bf16 v[32:35], v[164:167], v[188:191], v[32:35]
	v_mfma_f32_16x16x32_bf16 v[28:31], v[172:175], v[188:191], v[28:31]
	v_mfma_f32_16x16x32_bf16 v[16:19], v[164:167], v[196:199], v[16:19]
	v_mfma_f32_16x16x32_bf16 v[12:15], v[172:175], v[196:199], v[12:15]
	v_mfma_f32_16x16x32_bf16 v[8:11], v[164:167], v[204:207], v[8:11]
	v_mfma_f32_16x16x32_bf16 v[4:7], v[172:175], v[204:207], v[4:7]
	v_mfma_f32_16x16x32_bf16 v[36:39], v[164:167], v[180:183], v[52:55]
	v_mfma_f32_16x16x32_bf16 v[48:51], v[176:179], v[184:187], v[48:51]
	v_mfma_f32_16x16x32_bf16 v[32:35], v[168:171], v[192:195], v[32:35]
	v_mfma_f32_16x16x32_bf16 v[28:31], v[176:179], v[192:195], v[28:31]
	v_mfma_f32_16x16x32_bf16 v[16:19], v[168:171], v[200:203], v[16:19]
	v_mfma_f32_16x16x32_bf16 v[12:15], v[176:179], v[200:203], v[12:15]
	v_mfma_f32_16x16x32_bf16 v[8:11], v[168:171], v[208:211], v[8:11]
	v_mfma_f32_16x16x32_bf16 v[4:7], v[176:179], v[208:211], v[4:7]
	v_mfma_f32_16x16x32_bf16 v[36:39], v[168:171], v[184:187], v[36:39]
	s_setprio 0
	s_barrier
	s_add_i32 s68, 0, 0x18000
	v_add_u32_e32 v151, s68, v148
	s_add_i32 s69, 0, 0x1c000
	ds_read_b128 v[52:55], v151
	ds_read_b128 v[152:155], v151 offset:1024
	ds_read_b128 v[156:159], v151 offset:2048
	ds_read_b128 v[160:163], v151 offset:3072
	v_add_u32_e32 v151, s69, v148
	ds_read_b128 v[164:167], v151
	ds_read_b128 v[168:171], v151 offset:1024
	ds_read_b128 v[172:175], v151 offset:2048
	ds_read_b128 v[176:179], v151 offset:3072
	s_add_u32 s28, s28, 0x4000
	s_addc_u32 s29, s29, 0
	s_mov_b32 m0, s36
	ds_read_b128 v[180:183], v150 offset:32768
	ds_read_b128 v[184:187], v150 offset:33792
	ds_read_b128 v[188:191], v150 offset:34816
	ds_read_b128 v[192:195], v150 offset:35840
	ds_read_b128 v[196:199], v150 offset:36864
	ds_read_b128 v[200:203], v150 offset:37888
	ds_read_b128 v[204:207], v150 offset:38912
	ds_read_b128 v[208:211], v150 offset:39936
	global_load_lds_dwordx4 v136, s[28:29]
	s_mov_b32 m0, s37
	s_nop 0
	global_load_lds_dwordx4 v140, s[28:29]
	s_waitcnt vmcnt(8)
	s_waitcnt lgkmcnt(0)
	v_mfma_f32_16x16x32_bf16 v[132:135], v[52:55], v[180:183], v[132:135]
	v_mfma_f32_16x16x32_bf16 v[128:131], v[156:159], v[180:183], v[128:131]
	v_mfma_f32_16x16x32_bf16 v[124:127], v[52:55], v[188:191], v[124:127]
	v_mfma_f32_16x16x32_bf16 v[120:123], v[156:159], v[188:191], v[120:123]
	s_barrier
	s_setprio 1
	v_mfma_f32_16x16x32_bf16 v[108:111], v[52:55], v[196:199], v[108:111]
	v_mfma_f32_16x16x32_bf16 v[104:107], v[156:159], v[196:199], v[104:107]
	v_mfma_f32_16x16x32_bf16 v[92:95], v[52:55], v[204:207], v[92:95]
	v_mfma_f32_16x16x32_bf16 v[88:91], v[156:159], v[204:207], v[88:91]
	v_mfma_f32_16x16x32_bf16 v[132:135], v[152:155], v[184:187], v[132:135]
	v_mfma_f32_16x16x32_bf16 v[128:131], v[160:163], v[184:187], v[128:131]
	v_mfma_f32_16x16x32_bf16 v[124:127], v[152:155], v[192:195], v[124:127]
	v_mfma_f32_16x16x32_bf16 v[120:123], v[160:163], v[192:195], v[120:123]
	v_mfma_f32_16x16x32_bf16 v[108:111], v[152:155], v[200:203], v[108:111]
	v_mfma_f32_16x16x32_bf16 v[104:107], v[160:163], v[200:203], v[104:107]
	v_mfma_f32_16x16x32_bf16 v[92:95], v[152:155], v[208:211], v[92:95]
	v_mfma_f32_16x16x32_bf16 v[88:91], v[160:163], v[208:211], v[88:91]
	v_mfma_f32_16x16x32_bf16 v[116:119], v[164:167], v[180:183], v[116:119]
	v_mfma_f32_16x16x32_bf16 v[112:115], v[172:175], v[180:183], v[112:115]
	v_mfma_f32_16x16x32_bf16 v[100:103], v[164:167], v[188:191], v[100:103]
	v_mfma_f32_16x16x32_bf16 v[96:99], v[172:175], v[188:191], v[96:99]
	v_mfma_f32_16x16x32_bf16 v[84:87], v[164:167], v[196:199], v[84:87]
	v_mfma_f32_16x16x32_bf16 v[80:83], v[172:175], v[196:199], v[80:83]
	v_mfma_f32_16x16x32_bf16 v[76:79], v[164:167], v[204:207], v[76:79]
	v_mfma_f32_16x16x32_bf16 v[72:75], v[172:175], v[204:207], v[72:75]
	v_mfma_f32_16x16x32_bf16 v[116:119], v[168:171], v[184:187], v[116:119]
	v_mfma_f32_16x16x32_bf16 v[112:115], v[176:179], v[184:187], v[112:115]
	v_mfma_f32_16x16x32_bf16 v[100:103], v[168:171], v[192:195], v[100:103]
	v_mfma_f32_16x16x32_bf16 v[96:99], v[176:179], v[192:195], v[96:99]
	v_mfma_f32_16x16x32_bf16 v[84:87], v[168:171], v[200:203], v[84:87]
	v_mfma_f32_16x16x32_bf16 v[80:83], v[176:179], v[200:203], v[80:83]
	v_mfma_f32_16x16x32_bf16 v[76:79], v[168:171], v[208:211], v[76:79]
	v_mfma_f32_16x16x32_bf16 v[72:75], v[176:179], v[208:211], v[72:75]
	s_setprio 0
	s_barrier
; #define PG8_STAGE(bufoff, gbase, voff) do { _Pragma("unroll") for (int _i = 0; _i < 2; ++_i) \
;         __builtin_amdgcn_global_load_lds((const unsigned*)((const char*)(gbase) + (voff)[_i]), (PG8_LAS unsigned*)(lds + (bufoff) + ldsw + _i * 8192), 16, 0, 0); } while (0)
; #define PG8_LDA(dst, b, h) do { _Pragma("unroll") for (int m = 0; m < 4; ++m) _Pragma("unroll") for (int k = 0; k < 2; ++k) dst[m][k] = *(const PG8_LAS bf16x8*)(lds + PG8_SA(b, h) + aoff + m * 2048 + k * 1024); } while (0)
; #define PG8_MMA(ai, bj, At, Bt) do { __builtin_amdgcn_s_setprio(1); _Pragma("unroll") for (int m = 0; m < 4; ++m) _Pragma("unroll") for (int n = 0; n < 2; ++n) _Pragma("unroll") for (int k = 0; k < 2; ++k) \
;         acc[ai][bj][m][n] = __builtin_amdgcn_mfma_f32_16x16x32_bf16(Bt[n][k], At[m][k], acc[ai][bj][m][n], 0, 0, 0); __builtin_amdgcn_s_setprio(0); } while (0)
; #define PG8_WAIT_V(n) asm volatile("s_waitcnt vmcnt(" #n ")" ::: "memory")
; #define PG8_WAIT_L(n) asm volatile("s_waitcnt lgkmcnt(" #n ")" ::: "memory")
; #define PG8_BAR __builtin_amdgcn_s_barrier()
; #define PG8_SCHED __builtin_amdgcn_sched_barrier(0)
; template <class Epi, class Sched, bool ALIGN_EPI = false, bool SP2 = false, bool ABLK = false, bool BBLK = false>
; __device__ __forceinline__ void gemm_phase(PG8_LAS unsigned char* lds, const Gemm g, const Sched& S, const Epi& E) {
;     ...
;         for (int t = 0; t < nt; t += 2) {
;             const bool last = (t == nt - 2);
;             const char* a1 = cA + (size_t)(t + 1) * kstepA;
;             const char* a2 = last ? nA : cA + (size_t)(t + 2) * kstepA; const char* b2 = last ? nB : cB + (size_t)(t + 2) * kstepB;
;     ...
;             PG8_LDA(At, 1, 1); PG8_STAGE(PG8_SB(1, 0), b3, voffB); PG8_STAGE(PG8_SB(1, 1), b3 + hstepB, voffB); PG8_STAGE(PG8_SA(1, 0), a3, voffA);
;             PG8_WAIT_V(8); PG8_WAIT_L(0); PG8_BAR; PG8_MMA(1, 0, At, B0); PG8_MMA(1, 1, At, B1); PG8_BAR; PG8_SCHED;
;     ...
;         if constexpr (ALIGN_EPI) { if (wr == 0) PG8_BAR; }
	s_add_u32 s28, s26, 0x8000
	s_addc_u32 s29, s27, 0
	s_add_i32 s68, s68, s34
	s_mov_b32 m0, s68
	ds_read_b128 v[180:183], v150 offset:49152
	ds_read_b128 v[184:187], v150 offset:50176
	ds_read_b128 v[188:191], v150 offset:51200
	ds_read_b128 v[192:195], v150 offset:52224
	ds_read_b128 v[196:199], v150 offset:53248
	ds_read_b128 v[200:203], v150 offset:54272
	ds_read_b128 v[204:207], v150 offset:55296
	ds_read_b128 v[208:211], v150 offset:56320
	global_load_lds_dwordx4 v138, s[28:29]
	s_add_i32 m0, s68, 0x2000
	s_add_u32 s26, s26, 0xc000
	s_addc_u32 s27, s27, 0
	global_load_lds_dwordx4 v142, s[28:29]
	s_add_i32 s28, s69, s34
	s_mov_b32 m0, s28
	s_nop 0
	global_load_lds_dwordx4 v138, s[26:27]
	s_add_i32 m0, s28, 0x2000
	s_nop 0
	global_load_lds_dwordx4 v142, s[26:27]
	s_mov_b32 m0, s64
	s_nop 0
	global_load_lds_dwordx4 v136, s[24:25]
	s_mov_b32 m0, s65
	s_nop 0
	global_load_lds_dwordx4 v140, s[24:25]
	s_waitcnt vmcnt(8)
	s_waitcnt lgkmcnt(0)
	v_mfma_f32_16x16x32_bf16 v[68:71], v[52:55], v[180:183], v[68:71]
	v_mfma_f32_16x16x32_bf16 v[64:67], v[156:159], v[180:183], v[64:67]
	v_mfma_f32_16x16x32_bf16 v[60:63], v[52:55], v[188:191], v[60:63]
	v_mfma_f32_16x16x32_bf16 v[56:59], v[156:159], v[188:191], v[56:59]
	s_barrier
	s_setprio 1
	v_mfma_f32_16x16x32_bf16 v[44:47], v[52:55], v[196:199], v[44:47]
	v_mfma_f32_16x16x32_bf16 v[40:43], v[156:159], v[196:199], v[40:43]
	v_mfma_f32_16x16x32_bf16 v[24:27], v[52:55], v[204:207], v[24:27]
	v_mfma_f32_16x16x32_bf16 v[20:23], v[156:159], v[204:207], v[20:23]
	v_mfma_f32_16x16x32_bf16 v[68:71], v[152:155], v[184:187], v[68:71]
	v_mfma_f32_16x16x32_bf16 v[64:67], v[160:163], v[184:187], v[64:67]
	v_mfma_f32_16x16x32_bf16 v[60:63], v[152:155], v[192:195], v[60:63]
	v_mfma_f32_16x16x32_bf16 v[56:59], v[160:163], v[192:195], v[56:59]
	v_mfma_f32_16x16x32_bf16 v[44:47], v[152:155], v[200:203], v[44:47]
	v_mfma_f32_16x16x32_bf16 v[40:43], v[160:163], v[200:203], v[40:43]
	v_mfma_f32_16x16x32_bf16 v[24:27], v[152:155], v[208:211], v[24:27]
	v_mfma_f32_16x16x32_bf16 v[20:23], v[160:163], v[208:211], v[20:23]
	v_mfma_f32_16x16x32_bf16 v[36:39], v[164:167], v[180:183], v[36:39]
	v_mfma_f32_16x16x32_bf16 v[52:55], v[168:171], v[184:187], v[36:39]
	v_mfma_f32_16x16x32_bf16 v[36:39], v[172:175], v[180:183], v[48:51]
	v_mfma_f32_16x16x32_bf16 v[32:35], v[164:167], v[188:191], v[32:35]
	v_mfma_f32_16x16x32_bf16 v[28:31], v[172:175], v[188:191], v[28:31]
	v_mfma_f32_16x16x32_bf16 v[16:19], v[164:167], v[196:199], v[16:19]
	v_mfma_f32_16x16x32_bf16 v[12:15], v[172:175], v[196:199], v[12:15]
	v_mfma_f32_16x16x32_bf16 v[8:11], v[164:167], v[204:207], v[8:11]
	v_mfma_f32_16x16x32_bf16 v[4:7], v[172:175], v[204:207], v[4:7]
	v_mfma_f32_16x16x32_bf16 v[48:51], v[176:179], v[184:187], v[36:39]
	v_mfma_f32_16x16x32_bf16 v[32:35], v[168:171], v[192:195], v[32:35]
	v_mfma_f32_16x16x32_bf16 v[28:31], v[176:179], v[192:195], v[28:31]
	v_mfma_f32_16x16x32_bf16 v[16:19], v[168:171], v[200:203], v[16:19]
	v_mfma_f32_16x16x32_bf16 v[12:15], v[176:179], v[200:203], v[12:15]
	v_mfma_f32_16x16x32_bf16 v[8:11], v[168:171], v[208:211], v[8:11]
	v_mfma_f32_16x16x32_bf16 v[4:7], v[176:179], v[208:211], v[4:7]
	s_setprio 0
	s_barrier
	s_add_i32 s13, s13, 2
	s_add_u32 s22, s22, 0x10000
	s_addc_u32 s23, s23, 0
	s_add_u32 s82, s82, 0x10000
	s_addc_u32 vcc_lo, vcc_lo, 0
	s_cmp_gt_u32 s13, 29
	s_cbranch_scc0 .LBB0_2111
	s_and_b64 vcc, exec, s[6:7]
	s_movk_i32 s77, 0x1000
	s_cbranch_vccz .LBB0_2114
	s_barrier
